# adds removal of redundant store-drain vmcnt(0) waits in the proj (gate path) and up-conv GEMM epilogues (one wait after the bias / conv-weight loads kept)
# speedup vs baseline: 1.0013x; 1.0013x over previous
; DI float fsigmoid(float x) { return __builtin_amdgcn_rcpf(1.f + __expf(-x)); }
;     DI void operator()(const f32x4 (&acc)[2][2][4][2], const pg8::Unit& u, int wr, int wc, int fr, int fq) const {
;     ...
;                     f32x4 v0 = acc[ai][bj][m][0], v1 = acc[ai][bj][m][1];
;                     if (gate) { v0 = v0 + b0; v1 = v1 + b1;
; #pragma unroll
;                         for (int e = 0; e < 4; ++e) { v0[e] = fsigmoid(v0[e]); v1[e] = fsigmoid(v1[e]); } }
.LBB0_145:
	s_andn2_b64 vcc, exec, s[34:35]
	s_cbranch_vccnz .LBB0_147
	v_pk_add_f32 v[118:119], v[118:119], v[122:123]
	v_pk_add_f32 v[116:117], v[116:117], v[120:121]
	v_pk_add_f32 v[112:113], v[112:113], v[124:125]
	v_pk_add_f32 v[114:115], v[114:115], v[126:127]
	v_mul_f32_e32 v116, 0xbfb8aa3b, v116
	v_mul_f32_e32 v112, 0xbfb8aa3b, v112
	v_mul_f32_e32 v117, 0xbfb8aa3b, v117
	v_mul_f32_e32 v113, 0xbfb8aa3b, v113
	v_mul_f32_e32 v118, 0xbfb8aa3b, v118
	v_mul_f32_e32 v114, 0xbfb8aa3b, v114
	v_mul_f32_e32 v119, 0xbfb8aa3b, v119
	v_mul_f32_e32 v115, 0xbfb8aa3b, v115
	v_exp_f32_e32 v116, v116
	v_exp_f32_e32 v112, v112
	v_exp_f32_e32 v117, v117
	v_exp_f32_e32 v113, v113
	v_exp_f32_e32 v118, v118
	v_exp_f32_e32 v114, v114
	v_exp_f32_e32 v119, v119
	v_exp_f32_e32 v115, v115
	v_add_f32_e32 v116, 1.0, v116
	v_add_f32_e32 v112, 1.0, v112
	v_add_f32_e32 v117, 1.0, v117
	v_add_f32_e32 v113, 1.0, v113
	v_add_f32_e32 v118, 1.0, v118
	v_add_f32_e32 v114, 1.0, v114
	v_add_f32_e32 v119, 1.0, v119
	v_add_f32_e32 v115, 1.0, v115
	v_rcp_f32_e32 v116, v116
	v_rcp_f32_e32 v112, v112
	v_rcp_f32_e32 v117, v117
	v_rcp_f32_e32 v113, v113
	v_rcp_f32_e32 v118, v118
	v_rcp_f32_e32 v114, v114
	v_rcp_f32_e32 v119, v119
	v_rcp_f32_e32 v115, v115

; DI float fsigmoid(float x) { return __builtin_amdgcn_rcpf(1.f + __expf(-x)); }
;     DI void operator()(const f32x4 (&acc)[2][2][4][2], const pg8::Unit& u, int wr, int wc, int fr, int fq) const {
;     ...
;                     f32x4 v0 = acc[ai][bj][m][0], v1 = acc[ai][bj][m][1];
;                     if (gate) { v0 = v0 + b0; v1 = v1 + b1;
; #pragma unroll
;                         for (int e = 0; e < 4; ++e) { v0[e] = fsigmoid(v0[e]); v1[e] = fsigmoid(v1[e]); } }
.LBB0_149:
	s_andn2_b64 vcc, exec, s[34:35]
	s_cbranch_vccnz .LBB0_151
	v_pk_add_f32 v[110:111], v[110:111], v[122:123]
	v_pk_add_f32 v[108:109], v[108:109], v[120:121]
	v_pk_add_f32 v[104:105], v[104:105], v[124:125]
	v_pk_add_f32 v[106:107], v[106:107], v[126:127]
	v_mul_f32_e32 v108, 0xbfb8aa3b, v108
	v_mul_f32_e32 v104, 0xbfb8aa3b, v104
	v_mul_f32_e32 v109, 0xbfb8aa3b, v109
	v_mul_f32_e32 v105, 0xbfb8aa3b, v105
	v_mul_f32_e32 v110, 0xbfb8aa3b, v110
	v_mul_f32_e32 v106, 0xbfb8aa3b, v106
	v_mul_f32_e32 v111, 0xbfb8aa3b, v111
	v_mul_f32_e32 v107, 0xbfb8aa3b, v107
	v_exp_f32_e32 v108, v108
	v_exp_f32_e32 v104, v104
	v_exp_f32_e32 v109, v109
	v_exp_f32_e32 v105, v105
	v_exp_f32_e32 v110, v110
	v_exp_f32_e32 v106, v106
	v_exp_f32_e32 v111, v111
	v_exp_f32_e32 v107, v107
	v_add_f32_e32 v108, 1.0, v108
	v_add_f32_e32 v104, 1.0, v104
	v_add_f32_e32 v109, 1.0, v109
	v_add_f32_e32 v105, 1.0, v105
	v_add_f32_e32 v110, 1.0, v110
	v_add_f32_e32 v106, 1.0, v106
	v_add_f32_e32 v111, 1.0, v111
	v_add_f32_e32 v107, 1.0, v107
	v_rcp_f32_e32 v108, v108
	v_rcp_f32_e32 v104, v104
	v_rcp_f32_e32 v109, v109
	v_rcp_f32_e32 v105, v105
	v_rcp_f32_e32 v110, v110
	v_rcp_f32_e32 v106, v106
	v_rcp_f32_e32 v111, v111
	v_rcp_f32_e32 v107, v107

; DI float fsigmoid(float x) { return __builtin_amdgcn_rcpf(1.f + __expf(-x)); }
;     DI void operator()(const f32x4 (&acc)[2][2][4][2], const pg8::Unit& u, int wr, int wc, int fr, int fq) const {
;     ...
;                     f32x4 v0 = acc[ai][bj][m][0], v1 = acc[ai][bj][m][1];
;                     if (gate) { v0 = v0 + b0; v1 = v1 + b1;
; #pragma unroll
;                         for (int e = 0; e < 4; ++e) { v0[e] = fsigmoid(v0[e]); v1[e] = fsigmoid(v1[e]); } }
.LBB0_153:
	s_andn2_b64 vcc, exec, s[34:35]
	s_cbranch_vccnz .LBB0_155
	v_pk_add_f32 v[102:103], v[102:103], v[122:123]
	v_pk_add_f32 v[100:101], v[100:101], v[120:121]
	v_pk_add_f32 v[96:97], v[96:97], v[124:125]
	v_pk_add_f32 v[98:99], v[98:99], v[126:127]
	v_mul_f32_e32 v100, 0xbfb8aa3b, v100
	v_mul_f32_e32 v96, 0xbfb8aa3b, v96
	v_mul_f32_e32 v101, 0xbfb8aa3b, v101
	v_mul_f32_e32 v97, 0xbfb8aa3b, v97
	v_mul_f32_e32 v102, 0xbfb8aa3b, v102
	v_mul_f32_e32 v98, 0xbfb8aa3b, v98
	v_mul_f32_e32 v103, 0xbfb8aa3b, v103
	v_mul_f32_e32 v99, 0xbfb8aa3b, v99
	v_exp_f32_e32 v100, v100
	v_exp_f32_e32 v96, v96
	v_exp_f32_e32 v101, v101
	v_exp_f32_e32 v97, v97
	v_exp_f32_e32 v102, v102
	v_exp_f32_e32 v98, v98
	v_exp_f32_e32 v103, v103
	v_exp_f32_e32 v99, v99
	v_add_f32_e32 v100, 1.0, v100
	v_add_f32_e32 v96, 1.0, v96
	v_add_f32_e32 v101, 1.0, v101
	v_add_f32_e32 v97, 1.0, v97
	v_add_f32_e32 v102, 1.0, v102
	v_add_f32_e32 v98, 1.0, v98
	v_add_f32_e32 v103, 1.0, v103
	v_add_f32_e32 v99, 1.0, v99
	v_rcp_f32_e32 v100, v100
	v_rcp_f32_e32 v96, v96
	v_rcp_f32_e32 v101, v101
	v_rcp_f32_e32 v97, v97
	v_rcp_f32_e32 v102, v102
	v_rcp_f32_e32 v98, v98
	v_rcp_f32_e32 v103, v103
	v_rcp_f32_e32 v99, v99

; DI float fsigmoid(float x) { return __builtin_amdgcn_rcpf(1.f + __expf(-x)); }
;     DI void operator()(const f32x4 (&acc)[2][2][4][2], const pg8::Unit& u, int wr, int wc, int fr, int fq) const {
;     ...
;                     f32x4 v0 = acc[ai][bj][m][0], v1 = acc[ai][bj][m][1];
;                     if (gate) { v0 = v0 + b0; v1 = v1 + b1;
; #pragma unroll
;                         for (int e = 0; e < 4; ++e) { v0[e] = fsigmoid(v0[e]); v1[e] = fsigmoid(v1[e]); } }
.LBB0_157:
	s_andn2_b64 vcc, exec, s[34:35]
	s_cbranch_vccnz .LBB0_159
	v_pk_add_f32 v[94:95], v[94:95], v[122:123]
	v_pk_add_f32 v[92:93], v[92:93], v[120:121]
	v_pk_add_f32 v[88:89], v[88:89], v[124:125]
	v_pk_add_f32 v[90:91], v[90:91], v[126:127]
	v_mul_f32_e32 v92, 0xbfb8aa3b, v92
	v_mul_f32_e32 v88, 0xbfb8aa3b, v88
	v_mul_f32_e32 v93, 0xbfb8aa3b, v93
	v_mul_f32_e32 v89, 0xbfb8aa3b, v89
	v_mul_f32_e32 v94, 0xbfb8aa3b, v94
	v_mul_f32_e32 v90, 0xbfb8aa3b, v90
	v_mul_f32_e32 v95, 0xbfb8aa3b, v95
	v_mul_f32_e32 v91, 0xbfb8aa3b, v91
	v_exp_f32_e32 v92, v92
	v_exp_f32_e32 v88, v88
	v_exp_f32_e32 v93, v93
	v_exp_f32_e32 v89, v89
	v_exp_f32_e32 v94, v94
	v_exp_f32_e32 v90, v90
	v_exp_f32_e32 v95, v95
	v_exp_f32_e32 v91, v91
	v_add_f32_e32 v92, 1.0, v92
	v_add_f32_e32 v88, 1.0, v88
	v_add_f32_e32 v93, 1.0, v93
	v_add_f32_e32 v89, 1.0, v89
	v_add_f32_e32 v94, 1.0, v94
	v_add_f32_e32 v90, 1.0, v90
	v_add_f32_e32 v95, 1.0, v95
	v_add_f32_e32 v91, 1.0, v91
	v_rcp_f32_e32 v92, v92
	v_rcp_f32_e32 v88, v88
	v_rcp_f32_e32 v93, v93
	v_rcp_f32_e32 v89, v89
	v_rcp_f32_e32 v94, v94
	v_rcp_f32_e32 v90, v90
	v_rcp_f32_e32 v95, v95
	v_rcp_f32_e32 v91, v91

; DI float fsigmoid(float x) { return __builtin_amdgcn_rcpf(1.f + __expf(-x)); }
;     DI void operator()(const f32x4 (&acc)[2][2][4][2], const pg8::Unit& u, int wr, int wc, int fr, int fq) const {
;     ...
;                     f32x4 v0 = acc[ai][bj][m][0], v1 = acc[ai][bj][m][1];
;                     if (gate) { v0 = v0 + b0; v1 = v1 + b1;
; #pragma unroll
;                         for (int e = 0; e < 4; ++e) { v0[e] = fsigmoid(v0[e]); v1[e] = fsigmoid(v1[e]); } }
.LBB0_161:
	s_andn2_b64 vcc, exec, s[34:35]
	s_cbranch_vccnz .LBB0_163
	v_pk_add_f32 v[86:87], v[86:87], v[122:123]
	v_pk_add_f32 v[84:85], v[84:85], v[120:121]
	v_pk_add_f32 v[80:81], v[80:81], v[124:125]
	v_pk_add_f32 v[82:83], v[82:83], v[126:127]
	v_mul_f32_e32 v84, 0xbfb8aa3b, v84
	v_mul_f32_e32 v80, 0xbfb8aa3b, v80
	v_mul_f32_e32 v85, 0xbfb8aa3b, v85
	v_mul_f32_e32 v81, 0xbfb8aa3b, v81
	v_mul_f32_e32 v86, 0xbfb8aa3b, v86
	v_mul_f32_e32 v82, 0xbfb8aa3b, v82
	v_mul_f32_e32 v87, 0xbfb8aa3b, v87
	v_mul_f32_e32 v83, 0xbfb8aa3b, v83
	v_exp_f32_e32 v84, v84
	v_exp_f32_e32 v80, v80
	v_exp_f32_e32 v85, v85
	v_exp_f32_e32 v81, v81
	v_exp_f32_e32 v86, v86
	v_exp_f32_e32 v82, v82
	v_exp_f32_e32 v87, v87
	v_exp_f32_e32 v83, v83
	v_add_f32_e32 v84, 1.0, v84
	v_add_f32_e32 v80, 1.0, v80
	v_add_f32_e32 v85, 1.0, v85
	v_add_f32_e32 v81, 1.0, v81
	v_add_f32_e32 v86, 1.0, v86
	v_add_f32_e32 v82, 1.0, v82
	v_add_f32_e32 v87, 1.0, v87
	v_add_f32_e32 v83, 1.0, v83
	v_rcp_f32_e32 v84, v84
	v_rcp_f32_e32 v80, v80
	v_rcp_f32_e32 v85, v85
	v_rcp_f32_e32 v81, v81
	v_rcp_f32_e32 v86, v86
	v_rcp_f32_e32 v82, v82
	v_rcp_f32_e32 v87, v87
	v_rcp_f32_e32 v83, v83

; DI float fsigmoid(float x) { return __builtin_amdgcn_rcpf(1.f + __expf(-x)); }
;     DI void operator()(const f32x4 (&acc)[2][2][4][2], const pg8::Unit& u, int wr, int wc, int fr, int fq) const {
;     ...
;                     f32x4 v0 = acc[ai][bj][m][0], v1 = acc[ai][bj][m][1];
;                     if (gate) { v0 = v0 + b0; v1 = v1 + b1;
; #pragma unroll
;                         for (int e = 0; e < 4; ++e) { v0[e] = fsigmoid(v0[e]); v1[e] = fsigmoid(v1[e]); } }
.LBB0_165:
	s_andn2_b64 vcc, exec, s[34:35]
	s_cbranch_vccnz .LBB0_167
	v_pk_add_f32 v[78:79], v[78:79], v[122:123]
	v_pk_add_f32 v[76:77], v[76:77], v[120:121]
	v_pk_add_f32 v[72:73], v[72:73], v[124:125]
	v_pk_add_f32 v[74:75], v[74:75], v[126:127]
	v_mul_f32_e32 v76, 0xbfb8aa3b, v76
	v_mul_f32_e32 v72, 0xbfb8aa3b, v72
	v_mul_f32_e32 v77, 0xbfb8aa3b, v77
	v_mul_f32_e32 v73, 0xbfb8aa3b, v73
	v_mul_f32_e32 v78, 0xbfb8aa3b, v78
	v_mul_f32_e32 v74, 0xbfb8aa3b, v74
	v_mul_f32_e32 v79, 0xbfb8aa3b, v79
	v_mul_f32_e32 v75, 0xbfb8aa3b, v75
	v_exp_f32_e32 v76, v76
	v_exp_f32_e32 v72, v72
	v_exp_f32_e32 v77, v77
	v_exp_f32_e32 v73, v73
	v_exp_f32_e32 v78, v78
	v_exp_f32_e32 v74, v74
	v_exp_f32_e32 v79, v79
	v_exp_f32_e32 v75, v75
	v_add_f32_e32 v76, 1.0, v76
	v_add_f32_e32 v72, 1.0, v72
	v_add_f32_e32 v77, 1.0, v77
	v_add_f32_e32 v73, 1.0, v73
	v_add_f32_e32 v78, 1.0, v78
	v_add_f32_e32 v74, 1.0, v74
	v_add_f32_e32 v79, 1.0, v79
	v_add_f32_e32 v75, 1.0, v75
	v_rcp_f32_e32 v76, v76
	v_rcp_f32_e32 v72, v72
	v_rcp_f32_e32 v77, v77
	v_rcp_f32_e32 v73, v73
	v_rcp_f32_e32 v78, v78
	v_rcp_f32_e32 v74, v74
	v_rcp_f32_e32 v79, v79
	v_rcp_f32_e32 v75, v75

; DI float fsigmoid(float x) { return __builtin_amdgcn_rcpf(1.f + __expf(-x)); }
;     DI void operator()(const f32x4 (&acc)[2][2][4][2], const pg8::Unit& u, int wr, int wc, int fr, int fq) const {
;     ...
;                     f32x4 v0 = acc[ai][bj][m][0], v1 = acc[ai][bj][m][1];
;                     if (gate) { v0 = v0 + b0; v1 = v1 + b1;
; #pragma unroll
;                         for (int e = 0; e < 4; ++e) { v0[e] = fsigmoid(v0[e]); v1[e] = fsigmoid(v1[e]); } }
.LBB0_169:
	s_andn2_b64 vcc, exec, s[34:35]
	s_cbranch_vccnz .LBB0_171
	v_pk_add_f32 v[70:71], v[70:71], v[122:123]
	v_pk_add_f32 v[68:69], v[68:69], v[120:121]
	v_pk_add_f32 v[64:65], v[64:65], v[124:125]
	v_pk_add_f32 v[66:67], v[66:67], v[126:127]
	v_mul_f32_e32 v68, 0xbfb8aa3b, v68
	v_mul_f32_e32 v64, 0xbfb8aa3b, v64
	v_mul_f32_e32 v69, 0xbfb8aa3b, v69
	v_mul_f32_e32 v65, 0xbfb8aa3b, v65
	v_mul_f32_e32 v70, 0xbfb8aa3b, v70
	v_mul_f32_e32 v66, 0xbfb8aa3b, v66
	v_mul_f32_e32 v71, 0xbfb8aa3b, v71
	v_mul_f32_e32 v67, 0xbfb8aa3b, v67
	v_exp_f32_e32 v68, v68
	v_exp_f32_e32 v64, v64
	v_exp_f32_e32 v69, v69
	v_exp_f32_e32 v65, v65
	v_exp_f32_e32 v70, v70
	v_exp_f32_e32 v66, v66
	v_exp_f32_e32 v71, v71
	v_exp_f32_e32 v67, v67
	v_add_f32_e32 v68, 1.0, v68
	v_add_f32_e32 v64, 1.0, v64
	v_add_f32_e32 v69, 1.0, v69
	v_add_f32_e32 v65, 1.0, v65
	v_add_f32_e32 v70, 1.0, v70
	v_add_f32_e32 v66, 1.0, v66
	v_add_f32_e32 v71, 1.0, v71
	v_add_f32_e32 v67, 1.0, v67
	v_rcp_f32_e32 v68, v68
	v_rcp_f32_e32 v64, v64
	v_rcp_f32_e32 v69, v69
	v_rcp_f32_e32 v65, v65
	v_rcp_f32_e32 v70, v70
	v_rcp_f32_e32 v66, v66
	v_rcp_f32_e32 v71, v71
	v_rcp_f32_e32 v67, v67

; DI float fsigmoid(float x) { return __builtin_amdgcn_rcpf(1.f + __expf(-x)); }
;     DI void operator()(const f32x4 (&acc)[2][2][4][2], const pg8::Unit& u, int wr, int wc, int fr, int fq) const {
;     ...
;                     f32x4 v0 = acc[ai][bj][m][0], v1 = acc[ai][bj][m][1];
;                     if (gate) { v0 = v0 + b0; v1 = v1 + b1;
; #pragma unroll
;                         for (int e = 0; e < 4; ++e) { v0[e] = fsigmoid(v0[e]); v1[e] = fsigmoid(v1[e]); } }
.LBB0_179:
	s_andn2_b64 vcc, exec, s[34:35]
	s_cbranch_vccnz .LBB0_181
	v_pk_add_f32 v[54:55], v[54:55], v[66:67]
	v_pk_add_f32 v[52:53], v[52:53], v[64:65]
	v_pk_add_f32 v[48:49], v[48:49], v[68:69]
	v_pk_add_f32 v[50:51], v[50:51], v[70:71]
	v_mul_f32_e32 v52, 0xbfb8aa3b, v52
	v_mul_f32_e32 v48, 0xbfb8aa3b, v48
	v_mul_f32_e32 v53, 0xbfb8aa3b, v53
	v_mul_f32_e32 v49, 0xbfb8aa3b, v49
	v_mul_f32_e32 v54, 0xbfb8aa3b, v54
	v_mul_f32_e32 v50, 0xbfb8aa3b, v50
	v_mul_f32_e32 v55, 0xbfb8aa3b, v55
	v_mul_f32_e32 v51, 0xbfb8aa3b, v51
	v_exp_f32_e32 v52, v52
	v_exp_f32_e32 v48, v48
	v_exp_f32_e32 v53, v53
	v_exp_f32_e32 v49, v49
	v_exp_f32_e32 v54, v54
	v_exp_f32_e32 v50, v50
	v_exp_f32_e32 v55, v55
	v_exp_f32_e32 v51, v51
	v_add_f32_e32 v52, 1.0, v52
	v_add_f32_e32 v48, 1.0, v48
	v_add_f32_e32 v53, 1.0, v53
	v_add_f32_e32 v49, 1.0, v49
	v_add_f32_e32 v54, 1.0, v54
	v_add_f32_e32 v50, 1.0, v50
	v_add_f32_e32 v55, 1.0, v55
	v_add_f32_e32 v51, 1.0, v51
	v_rcp_f32_e32 v52, v52
	v_rcp_f32_e32 v48, v48
	v_rcp_f32_e32 v53, v53
	v_rcp_f32_e32 v49, v49
	v_rcp_f32_e32 v54, v54
	v_rcp_f32_e32 v50, v50
	v_rcp_f32_e32 v55, v55
	v_rcp_f32_e32 v51, v51

; DI float fsigmoid(float x) { return __builtin_amdgcn_rcpf(1.f + __expf(-x)); }
;     DI void operator()(const f32x4 (&acc)[2][2][4][2], const pg8::Unit& u, int wr, int wc, int fr, int fq) const {
;     ...
;                     f32x4 v0 = acc[ai][bj][m][0], v1 = acc[ai][bj][m][1];
;                     if (gate) { v0 = v0 + b0; v1 = v1 + b1;
; #pragma unroll
;                         for (int e = 0; e < 4; ++e) { v0[e] = fsigmoid(v0[e]); v1[e] = fsigmoid(v1[e]); } }
.LBB0_183:
	s_andn2_b64 vcc, exec, s[34:35]
	s_cbranch_vccnz .LBB0_185
	v_pk_add_f32 v[46:47], v[46:47], v[66:67]
	v_pk_add_f32 v[44:45], v[44:45], v[64:65]
	v_pk_add_f32 v[40:41], v[40:41], v[68:69]
	v_pk_add_f32 v[42:43], v[42:43], v[70:71]
	v_mul_f32_e32 v44, 0xbfb8aa3b, v44
	v_mul_f32_e32 v40, 0xbfb8aa3b, v40
	v_mul_f32_e32 v45, 0xbfb8aa3b, v45
	v_mul_f32_e32 v41, 0xbfb8aa3b, v41
	v_mul_f32_e32 v46, 0xbfb8aa3b, v46
	v_mul_f32_e32 v42, 0xbfb8aa3b, v42
	v_mul_f32_e32 v47, 0xbfb8aa3b, v47
	v_mul_f32_e32 v43, 0xbfb8aa3b, v43
	v_exp_f32_e32 v44, v44
	v_exp_f32_e32 v40, v40
	v_exp_f32_e32 v45, v45
	v_exp_f32_e32 v41, v41
	v_exp_f32_e32 v46, v46
	v_exp_f32_e32 v42, v42
	v_exp_f32_e32 v47, v47
	v_exp_f32_e32 v43, v43
	v_add_f32_e32 v44, 1.0, v44
	v_add_f32_e32 v40, 1.0, v40
	v_add_f32_e32 v45, 1.0, v45
	v_add_f32_e32 v41, 1.0, v41
	v_add_f32_e32 v46, 1.0, v46
	v_add_f32_e32 v42, 1.0, v42
	v_add_f32_e32 v47, 1.0, v47
	v_add_f32_e32 v43, 1.0, v43
	v_rcp_f32_e32 v44, v44
	v_rcp_f32_e32 v40, v40
	v_rcp_f32_e32 v45, v45
	v_rcp_f32_e32 v41, v41
	v_rcp_f32_e32 v46, v46
	v_rcp_f32_e32 v42, v42
	v_rcp_f32_e32 v47, v47
	v_rcp_f32_e32 v43, v43

; DI float fsigmoid(float x) { return __builtin_amdgcn_rcpf(1.f + __expf(-x)); }
;     DI void operator()(const f32x4 (&acc)[2][2][4][2], const pg8::Unit& u, int wr, int wc, int fr, int fq) const {
;     ...
;                     f32x4 v0 = acc[ai][bj][m][0], v1 = acc[ai][bj][m][1];
;                     if (gate) { v0 = v0 + b0; v1 = v1 + b1;
; #pragma unroll
;                         for (int e = 0; e < 4; ++e) { v0[e] = fsigmoid(v0[e]); v1[e] = fsigmoid(v1[e]); } }
.LBB0_187:
	s_andn2_b64 vcc, exec, s[34:35]
	s_cbranch_vccnz .LBB0_189
	v_pk_add_f32 v[38:39], v[38:39], v[66:67]
	v_pk_add_f32 v[36:37], v[36:37], v[64:65]
	v_pk_add_f32 v[32:33], v[32:33], v[68:69]
	v_pk_add_f32 v[34:35], v[34:35], v[70:71]
	v_mul_f32_e32 v36, 0xbfb8aa3b, v36
	v_mul_f32_e32 v32, 0xbfb8aa3b, v32
	v_mul_f32_e32 v37, 0xbfb8aa3b, v37
	v_mul_f32_e32 v33, 0xbfb8aa3b, v33
	v_mul_f32_e32 v38, 0xbfb8aa3b, v38
	v_mul_f32_e32 v34, 0xbfb8aa3b, v34
	v_mul_f32_e32 v39, 0xbfb8aa3b, v39
	v_mul_f32_e32 v35, 0xbfb8aa3b, v35
	v_exp_f32_e32 v36, v36
	v_exp_f32_e32 v32, v32
	v_exp_f32_e32 v37, v37
	v_exp_f32_e32 v33, v33
	v_exp_f32_e32 v38, v38
	v_exp_f32_e32 v34, v34
	v_exp_f32_e32 v39, v39
	v_exp_f32_e32 v35, v35
	v_add_f32_e32 v36, 1.0, v36
	v_add_f32_e32 v32, 1.0, v32
	v_add_f32_e32 v37, 1.0, v37
	v_add_f32_e32 v33, 1.0, v33
	v_add_f32_e32 v38, 1.0, v38
	v_add_f32_e32 v34, 1.0, v34
	v_add_f32_e32 v39, 1.0, v39
	v_add_f32_e32 v35, 1.0, v35
	v_rcp_f32_e32 v36, v36
	v_rcp_f32_e32 v32, v32
	v_rcp_f32_e32 v37, v37
	v_rcp_f32_e32 v33, v33
	v_rcp_f32_e32 v38, v38
	v_rcp_f32_e32 v34, v34
	v_rcp_f32_e32 v39, v39
	v_rcp_f32_e32 v35, v35

; DI float fsigmoid(float x) { return __builtin_amdgcn_rcpf(1.f + __expf(-x)); }
;     DI void operator()(const f32x4 (&acc)[2][2][4][2], const pg8::Unit& u, int wr, int wc, int fr, int fq) const {
;     ...
;                     f32x4 v0 = acc[ai][bj][m][0], v1 = acc[ai][bj][m][1];
;                     if (gate) { v0 = v0 + b0; v1 = v1 + b1;
; #pragma unroll
;                         for (int e = 0; e < 4; ++e) { v0[e] = fsigmoid(v0[e]); v1[e] = fsigmoid(v1[e]); } }
.LBB0_191:
	s_andn2_b64 vcc, exec, s[34:35]
	s_cbranch_vccnz .LBB0_193
	v_pk_add_f32 v[30:31], v[30:31], v[66:67]
	v_pk_add_f32 v[28:29], v[28:29], v[64:65]
	v_pk_add_f32 v[24:25], v[24:25], v[68:69]
	v_pk_add_f32 v[26:27], v[26:27], v[70:71]
	v_mul_f32_e32 v28, 0xbfb8aa3b, v28
	v_mul_f32_e32 v24, 0xbfb8aa3b, v24
	v_mul_f32_e32 v29, 0xbfb8aa3b, v29
	v_mul_f32_e32 v25, 0xbfb8aa3b, v25
	v_mul_f32_e32 v30, 0xbfb8aa3b, v30
	v_mul_f32_e32 v26, 0xbfb8aa3b, v26
	v_mul_f32_e32 v31, 0xbfb8aa3b, v31
	v_mul_f32_e32 v27, 0xbfb8aa3b, v27
	v_exp_f32_e32 v28, v28
	v_exp_f32_e32 v24, v24
	v_exp_f32_e32 v29, v29
	v_exp_f32_e32 v25, v25
	v_exp_f32_e32 v30, v30
	v_exp_f32_e32 v26, v26
	v_exp_f32_e32 v31, v31
	v_exp_f32_e32 v27, v27
	v_add_f32_e32 v28, 1.0, v28
	v_add_f32_e32 v24, 1.0, v24
	v_add_f32_e32 v29, 1.0, v29
	v_add_f32_e32 v25, 1.0, v25
	v_add_f32_e32 v30, 1.0, v30
	v_add_f32_e32 v26, 1.0, v26
	v_add_f32_e32 v31, 1.0, v31
	v_add_f32_e32 v27, 1.0, v27
	v_rcp_f32_e32 v28, v28
	v_rcp_f32_e32 v24, v24
	v_rcp_f32_e32 v29, v29
	v_rcp_f32_e32 v25, v25
	v_rcp_f32_e32 v30, v30
	v_rcp_f32_e32 v26, v26
	v_rcp_f32_e32 v31, v31
	v_rcp_f32_e32 v27, v27

; DI float fsigmoid(float x) { return __builtin_amdgcn_rcpf(1.f + __expf(-x)); }
;     DI void operator()(const f32x4 (&acc)[2][2][4][2], const pg8::Unit& u, int wr, int wc, int fr, int fq) const {
;     ...
;                     f32x4 v0 = acc[ai][bj][m][0], v1 = acc[ai][bj][m][1];
;                     if (gate) { v0 = v0 + b0; v1 = v1 + b1;
; #pragma unroll
;                         for (int e = 0; e < 4; ++e) { v0[e] = fsigmoid(v0[e]); v1[e] = fsigmoid(v1[e]); } }
.LBB0_195:
	s_andn2_b64 vcc, exec, s[34:35]
	s_cbranch_vccnz .LBB0_197
	v_pk_add_f32 v[22:23], v[22:23], v[66:67]
	v_pk_add_f32 v[20:21], v[20:21], v[64:65]
	v_pk_add_f32 v[16:17], v[16:17], v[68:69]
	v_pk_add_f32 v[18:19], v[18:19], v[70:71]
	v_mul_f32_e32 v20, 0xbfb8aa3b, v20
	v_mul_f32_e32 v16, 0xbfb8aa3b, v16
	v_mul_f32_e32 v21, 0xbfb8aa3b, v21
	v_mul_f32_e32 v17, 0xbfb8aa3b, v17
	v_mul_f32_e32 v22, 0xbfb8aa3b, v22
	v_mul_f32_e32 v18, 0xbfb8aa3b, v18
	v_mul_f32_e32 v23, 0xbfb8aa3b, v23
	v_mul_f32_e32 v19, 0xbfb8aa3b, v19
	v_exp_f32_e32 v20, v20
	v_exp_f32_e32 v16, v16
	v_exp_f32_e32 v21, v21
	v_exp_f32_e32 v17, v17
	v_exp_f32_e32 v22, v22
	v_exp_f32_e32 v18, v18
	v_exp_f32_e32 v23, v23
	v_exp_f32_e32 v19, v19
	v_add_f32_e32 v20, 1.0, v20
	v_add_f32_e32 v16, 1.0, v16
	v_add_f32_e32 v21, 1.0, v21
	v_add_f32_e32 v17, 1.0, v17
	v_add_f32_e32 v22, 1.0, v22
	v_add_f32_e32 v18, 1.0, v18
	v_add_f32_e32 v23, 1.0, v23
	v_add_f32_e32 v19, 1.0, v19
	v_rcp_f32_e32 v20, v20
	v_rcp_f32_e32 v16, v16
	v_rcp_f32_e32 v21, v21
	v_rcp_f32_e32 v17, v17
	v_rcp_f32_e32 v22, v22
	v_rcp_f32_e32 v18, v18
	v_rcp_f32_e32 v23, v23
	v_rcp_f32_e32 v19, v19

; DI float fsigmoid(float x) { return __builtin_amdgcn_rcpf(1.f + __expf(-x)); }
;     DI void operator()(const f32x4 (&acc)[2][2][4][2], const pg8::Unit& u, int wr, int wc, int fr, int fq) const {
;     ...
;                     f32x4 v0 = acc[ai][bj][m][0], v1 = acc[ai][bj][m][1];
;                     if (gate) { v0 = v0 + b0; v1 = v1 + b1;
; #pragma unroll
;                         for (int e = 0; e < 4; ++e) { v0[e] = fsigmoid(v0[e]); v1[e] = fsigmoid(v1[e]); } }
.LBB0_199:
	s_andn2_b64 vcc, exec, s[34:35]
	s_cbranch_vccnz .LBB0_201
	v_pk_add_f32 v[14:15], v[14:15], v[66:67]
	v_pk_add_f32 v[12:13], v[12:13], v[64:65]
	v_pk_add_f32 v[8:9], v[8:9], v[68:69]
	v_pk_add_f32 v[10:11], v[10:11], v[70:71]
	v_mul_f32_e32 v12, 0xbfb8aa3b, v12
	v_mul_f32_e32 v8, 0xbfb8aa3b, v8
	v_mul_f32_e32 v13, 0xbfb8aa3b, v13
	v_mul_f32_e32 v9, 0xbfb8aa3b, v9
	v_mul_f32_e32 v14, 0xbfb8aa3b, v14
	v_mul_f32_e32 v10, 0xbfb8aa3b, v10
	v_mul_f32_e32 v15, 0xbfb8aa3b, v15
	v_mul_f32_e32 v11, 0xbfb8aa3b, v11
	v_exp_f32_e32 v12, v12
	v_exp_f32_e32 v8, v8
	v_exp_f32_e32 v13, v13
	v_exp_f32_e32 v9, v9
	v_exp_f32_e32 v14, v14
	v_exp_f32_e32 v10, v10
	v_exp_f32_e32 v15, v15
	v_exp_f32_e32 v11, v11
	v_add_f32_e32 v12, 1.0, v12
	v_add_f32_e32 v8, 1.0, v8
	v_add_f32_e32 v13, 1.0, v13
	v_add_f32_e32 v9, 1.0, v9
	v_add_f32_e32 v14, 1.0, v14
	v_add_f32_e32 v10, 1.0, v10
	v_add_f32_e32 v15, 1.0, v15
	v_add_f32_e32 v11, 1.0, v11
	v_rcp_f32_e32 v12, v12
	v_rcp_f32_e32 v8, v8
	v_rcp_f32_e32 v13, v13
	v_rcp_f32_e32 v9, v9
	v_rcp_f32_e32 v14, v14
	v_rcp_f32_e32 v10, v10
	v_rcp_f32_e32 v15, v15
	v_rcp_f32_e32 v11, v11

; DI float fsigmoid(float x) { return __builtin_amdgcn_rcpf(1.f + __expf(-x)); }
;     DI void operator()(const f32x4 (&acc)[2][2][4][2], const pg8::Unit& u, int wr, int wc, int fr, int fq) const {
;     ...
;                     f32x4 v0 = acc[ai][bj][m][0], v1 = acc[ai][bj][m][1];
;                     if (gate) { v0 = v0 + b0; v1 = v1 + b1;
; #pragma unroll
;                         for (int e = 0; e < 4; ++e) { v0[e] = fsigmoid(v0[e]); v1[e] = fsigmoid(v1[e]); } }
.LBB0_203:
	s_andn2_b64 vcc, exec, s[34:35]
	s_cbranch_vccnz .LBB0_205
	v_pk_add_f32 v[6:7], v[6:7], v[66:67]
	v_pk_add_f32 v[4:5], v[4:5], v[64:65]
	v_pk_add_f32 v[0:1], v[0:1], v[68:69]
	v_pk_add_f32 v[2:3], v[2:3], v[70:71]
	v_mul_f32_e32 v4, 0xbfb8aa3b, v4
	v_mul_f32_e32 v0, 0xbfb8aa3b, v0
	v_mul_f32_e32 v5, 0xbfb8aa3b, v5
	v_mul_f32_e32 v1, 0xbfb8aa3b, v1
	v_mul_f32_e32 v6, 0xbfb8aa3b, v6
	v_mul_f32_e32 v2, 0xbfb8aa3b, v2
	v_mul_f32_e32 v7, 0xbfb8aa3b, v7
	v_mul_f32_e32 v3, 0xbfb8aa3b, v3
	v_exp_f32_e32 v4, v4
	v_exp_f32_e32 v0, v0
	v_exp_f32_e32 v5, v5
	v_exp_f32_e32 v1, v1
	v_exp_f32_e32 v6, v6
	v_exp_f32_e32 v2, v2
	v_exp_f32_e32 v7, v7
	v_exp_f32_e32 v3, v3
	v_add_f32_e32 v4, 1.0, v4
	v_add_f32_e32 v0, 1.0, v0
	v_add_f32_e32 v5, 1.0, v5
	v_add_f32_e32 v1, 1.0, v1
	v_add_f32_e32 v6, 1.0, v6
	v_add_f32_e32 v2, 1.0, v2
	v_add_f32_e32 v7, 1.0, v7
	v_add_f32_e32 v3, 1.0, v3
	v_rcp_f32_e32 v4, v4
	v_rcp_f32_e32 v0, v0
	v_rcp_f32_e32 v5, v5
	v_rcp_f32_e32 v1, v1
	v_rcp_f32_e32 v6, v6
	v_rcp_f32_e32 v2, v2
	v_rcp_f32_e32 v7, v7
	v_rcp_f32_e32 v3, v3

; DI u32x4 pack8(const float (&f)[8]) { u32x4 w; w.x = pk2(f[0], f[1]); w.y = pk2(f[2], f[3]); w.z = pk2(f[4], f[5]); w.w = pk2(f[6], f[7]); return w; }
; DI float fsilu(float x) { return x * fsigmoid(x); }
; DI float dpp_ror1(float v) { return __int_as_float(__builtin_amdgcn_update_dpp(0, __float_as_int(v), 0x121, 0xf, 0xf, false)); }
; DI float dpp_ror2(float v) { return __int_as_float(__builtin_amdgcn_update_dpp(0, __float_as_int(v), 0x122, 0xf, 0xf, false)); }
;     DI void operator()(const f32x4 (&acc)[2][2][4][2], const pg8::Unit& u, int wr, int wcv, int fr, int fq) const {
;     ...
;             for (int m = 0; m < 4; ++m) {
;                 const int lrow = 64 * blk + 16 * m + fr, t = 254 * u.pm - 2 + lrow, spos = t & 2047;
;                 float o[8], r1[8], r2[8];
; #pragma unroll
;                 for (int e = 0; e < 8; ++e) { const float uc = acc[ai][0][m][e >> 2][e & 3], gv = acc[ai][1][m][e >> 2][e & 3];
;                     r1[e] = dpp_ror1(uc); r2[e] = dpp_ror2(uc);
;                     float um1 = (fr >= 1) ? r1[e] : p1[e], um2 = (fr >= 2) ? r2[e] : p2[e];
;                     if (spos < 1) um1 = 0.f;
;                     if (spos < 2) um2 = 0.f;
;                     const float v = bb[e] + w0[e] * um2 + w1[e] * um1 + w2[e] * uc;
;                     o[e] = fsilu(v) * gv; }
; #pragma unroll
;                 for (int e = 0; e < 8; ++e) { p1[e] = r1[e]; p2[e] = r2[e]; }
;                 if (lrow >= 2 && t < T) *(u32x4*)(act + (size_t)t * DFF + ch0) = pack8(o);
.LBB0_883:
	s_waitcnt vmcnt(0)
	s_mul_i32 s53, s87, 0xfe
	s_add_i32 s53, s53, -2
	v_add_u32_e32 v239, s53, v180
	v_mov_b32_e32 v235, v197
	v_mov_b32_e32 v234, v197
	v_mov_b32_e32 v232, v197
	v_mov_b32_e32 v223, v197
	v_mov_b32_e32 v222, v197
	v_mov_b32_e32 v221, v197
	v_mov_b32_e32 v220, v197
	v_mov_b32_e32 v219, v197
	v_mov_b32_e32 v218, v197
	v_mov_b32_e32 v217, v197
	v_mov_b32_e32 v216, v197
	v_mov_b32_e32 v215, v197
	v_mov_b32_e32 v214, v197
	v_mov_b32_e32 v213, v197
	v_mov_b32_e32 v212, v197
	v_mov_b32_e32 v195, v197
	v_cmp_gt_i32_e32 vcc, s19, v239
	v_mov_b32_dpp v235, v156 row_ror:1 row_mask:0xf bank_mask:0xf
	v_mov_b32_dpp v234, v156 row_ror:2 row_mask:0xf bank_mask:0xf
	v_mov_b32_dpp v232, v157 row_ror:1 row_mask:0xf bank_mask:0xf
	v_mov_b32_dpp v223, v157 row_ror:2 row_mask:0xf bank_mask:0xf
	v_mov_b32_dpp v222, v158 row_ror:1 row_mask:0xf bank_mask:0xf
	v_mov_b32_dpp v221, v158 row_ror:2 row_mask:0xf bank_mask:0xf
	v_mov_b32_dpp v220, v159 row_ror:1 row_mask:0xf bank_mask:0xf
	v_mov_b32_dpp v219, v159 row_ror:2 row_mask:0xf bank_mask:0xf
	v_mov_b32_dpp v218, v148 row_ror:1 row_mask:0xf bank_mask:0xf
	v_mov_b32_dpp v217, v148 row_ror:2 row_mask:0xf bank_mask:0xf
	v_mov_b32_dpp v216, v149 row_ror:1 row_mask:0xf bank_mask:0xf
	v_mov_b32_dpp v215, v149 row_ror:2 row_mask:0xf bank_mask:0xf
	v_mov_b32_dpp v214, v150 row_ror:1 row_mask:0xf bank_mask:0xf
	v_mov_b32_dpp v213, v150 row_ror:2 row_mask:0xf bank_mask:0xf
	v_mov_b32_dpp v212, v151 row_ror:1 row_mask:0xf bank_mask:0xf
	v_mov_b32_dpp v195, v151 row_ror:2 row_mask:0xf bank_mask:0xf
	s_and_b64 s[50:51], s[44:45], vcc
	s_and_saveexec_b64 s[58:59], s[50:51]
	s_cbranch_execz .LBB0_885
	v_and_b32_e32 v204, 0x7ff, v239
	v_cndmask_b32_e64 v164, v235, v164, s[40:41]
	v_cmp_eq_u32_e32 vcc, 0, v204
	v_mov_b32_e32 v202, v156
	v_cndmask_b32_e64 v156, v243, v234, s[42:43]
	v_cmp_gt_u32_e64 s[50:51], 2, v204
	v_cndmask_b32_e64 v201, v164, 0, vcc
	v_mov_b32_e32 v203, v84
	v_mov_b32_e32 v200, v88
	v_cndmask_b32_e64 v156, v156, 0, s[50:51]
	v_pk_mul_f32 v[200:201], v[202:203], v[200:201]
	v_fma_f32 v156, v80, v156, v92
	v_add_f32_e32 v156, v201, v156
	v_add_f32_e32 v200, v200, v156
	v_mul_f32_e32 v156, 0xbfb8aa3b, v200
	v_exp_f32_e32 v201, v156
	v_cndmask_b32_e64 v156, v232, v165, s[40:41]
	v_cndmask_b32_e64 v165, v156, 0, vcc
	v_mov_b32_e32 v156, v157
	v_mov_b32_e32 v157, v85
	v_mov_b32_e32 v164, v89
	v_pk_mul_f32 v[156:157], v[156:157], v[164:165]
	v_cndmask_b32_e64 v164, v242, v223, s[42:43]
	v_cndmask_b32_e64 v164, v164, 0, s[50:51]
	v_fma_f32 v164, v81, v164, v93
	v_add_f32_e32 v157, v157, v164
	v_add_f32_e32 v156, v156, v157
	v_mul_f32_e32 v157, 0xbfb8aa3b, v156
	v_exp_f32_e32 v157, v157
	v_add_f32_e32 v164, 1.0, v201
	v_rcp_f32_e32 v164, v164
	v_mov_b32_e32 v165, v86
	v_add_f32_e32 v157, 1.0, v157
	v_rcp_f32_e32 v157, v157
	v_mul_f32_e32 v164, v200, v164
	v_mul_f32_e32 v200, v152, v164
	v_mov_b32_e32 v164, v158
	v_mul_f32_e32 v152, v156, v157
	v_cndmask_b32_e64 v156, v222, v166, s[40:41]
	v_cndmask_b32_e64 v158, v240, v221, s[42:43]
	v_cndmask_b32_e64 v157, v156, 0, vcc
	v_mov_b32_e32 v156, v90
	v_cndmask_b32_e64 v158, v158, 0, s[50:51]
	v_pk_mul_f32 v[156:157], v[164:165], v[156:157]
	v_fma_f32 v158, v82, v158, v94
	v_add_f32_e32 v157, v157, v158
	v_add_f32_e32 v164, v156, v157
	v_mul_f32_e32 v156, 0xbfb8aa3b, v164
	v_exp_f32_e32 v165, v156
	v_cndmask_b32_e64 v156, v220, v167, s[40:41]
	v_cndmask_b32_e64 v157, v156, 0, vcc
	v_mov_b32_e32 v158, v159
	v_mov_b32_e32 v159, v87
	v_mov_b32_e32 v156, v91
	v_pk_mul_f32 v[156:157], v[158:159], v[156:157]
	v_cndmask_b32_e64 v158, v237, v219, s[42:43]
	v_cndmask_b32_e64 v158, v158, 0, s[50:51]
	v_fma_f32 v158, v83, v158, v95
	v_add_f32_e32 v157, v157, v158
	v_add_f32_e32 v158, v156, v157
	v_mul_f32_e32 v156, 0xbfb8aa3b, v158
	v_exp_f32_e32 v156, v156
	v_mul_f32_e32 v159, v153, v152
	v_add_f32_e32 v152, 1.0, v165
	v_rcp_f32_e32 v165, v152
	v_add_f32_e32 v152, 1.0, v156
	v_rcp_f32_e32 v166, v152
	v_cndmask_b32_e64 v152, v218, v160, s[40:41]
	v_mov_b32_e32 v156, v148
	v_cndmask_b32_e64 v148, v241, v217, s[42:43]
	v_cndmask_b32_e64 v153, v152, 0, vcc
	v_mov_b32_e32 v157, v64
	v_mov_b32_e32 v152, v68
	v_cndmask_b32_e64 v148, v148, 0, s[50:51]
	v_pk_mul_f32 v[152:153], v[156:157], v[152:153]
	v_fma_f32 v148, v60, v148, v72
	v_add_f32_e32 v148, v153, v148
	v_add_f32_e32 v156, v152, v148
	v_mul_f32_e32 v148, 0xbfb8aa3b, v156
	v_exp_f32_e32 v148, v148
	v_mul_f32_e32 v152, v164, v165
	v_mul_f32_e32 v157, v158, v166
	v_mul_f32_e32 v154, v154, v152
	v_add_f32_e32 v148, 1.0, v148
	v_rcp_f32_e32 v158, v148
	v_cndmask_b32_e64 v148, v216, v161, s[40:41]
	v_cndmask_b32_e64 v153, v148, 0, vcc
	v_mov_b32_e32 v148, v149
	v_mov_b32_e32 v149, v65
	v_mov_b32_e32 v152, v69
	v_pk_mul_f32 v[148:149], v[148:149], v[152:153]
	v_cndmask_b32_e64 v152, v238, v215, s[42:43]
	v_cndmask_b32_e64 v152, v152, 0, s[50:51]
	v_fma_f32 v152, v61, v152, v73
	v_add_f32_e32 v149, v149, v152
	v_add_f32_e32 v160, v148, v149
	v_mul_f32_e32 v148, 0xbfb8aa3b, v160
	v_exp_f32_e32 v148, v148
	v_mul_f32_e32 v149, v156, v158
	v_mul_f32_e32 v156, v144, v149
	v_mov_b32_e32 v152, v150
	v_add_f32_e32 v144, 1.0, v148
	v_cndmask_b32_e64 v148, v214, v162, s[40:41]
	v_cndmask_b32_e64 v150, v236, v213, s[42:43]
	v_cndmask_b32_e64 v149, v148, 0, vcc
	v_mov_b32_e32 v153, v66
	v_mov_b32_e32 v148, v70
	v_cndmask_b32_e64 v150, v150, 0, s[50:51]
	v_pk_mul_f32 v[148:149], v[152:153], v[148:149]
	v_fma_f32 v150, v62, v150, v74
	v_add_f32_e32 v149, v149, v150
	v_add_f32_e32 v152, v148, v149
	v_mul_f32_e32 v148, 0xbfb8aa3b, v152
	v_exp_f32_e32 v153, v148
	v_cndmask_b32_e64 v148, v212, v163, s[40:41]
	v_cndmask_b32_e64 v149, v148, 0, vcc
	v_mov_b32_e32 v150, v151
	v_mov_b32_e32 v151, v67
	v_mov_b32_e32 v148, v71
	v_pk_mul_f32 v[148:149], v[150:151], v[148:149]
	v_cndmask_b32_e64 v150, v233, v195, s[42:43]
	v_cndmask_b32_e64 v150, v150, 0, s[50:51]
	v_fma_f32 v150, v63, v150, v75
	v_add_f32_e32 v149, v149, v150
	v_add_f32_e32 v148, v148, v149
	v_mul_f32_e32 v149, 0xbfb8aa3b, v148
	v_exp_f32_e32 v149, v149
	v_rcp_f32_e32 v144, v144
	v_add_f32_e32 v150, 1.0, v153
	v_rcp_f32_e32 v150, v150
	v_add_f32_e32 v149, 1.0, v149
	v_rcp_f32_e32 v149, v149
	v_mul_f32_e32 v144, v160, v144
	v_mul_f32_e32 v151, v145, v144
	v_mul_f32_e32 v144, v152, v150
	v_mul_f32_e32 v150, v146, v144
	v_mul_f32_e32 v144, v148, v149
	v_mov_b64_e32 v[148:149], s[4:5]
	s_movk_i32 s50, 0x1600
	v_mul_f32_e32 v155, v155, v157
	v_mul_f32_e32 v147, v147, v144
	v_mad_i64_i32 v[148:149], s[50:51], v239, s50, v[148:149]
	v_cvt_pk_bf16_f32 v144, v200, v159
	v_cvt_pk_bf16_f32 v145, v154, v155
	v_cvt_pk_bf16_f32 v146, v156, v151
	v_cvt_pk_bf16_f32 v147, v150, v147
	v_lshl_add_u64 v[148:149], v[178:179], 1, v[148:149]
	global_store_dwordx4 v[148:149], v[144:147], off
; DI u32x4 pack8(const float (&f)[8]) { u32x4 w; w.x = pk2(f[0], f[1]); w.y = pk2(f[2], f[3]); w.z = pk2(f[4], f[5]); w.w = pk2(f[6], f[7]); return w; }
; DI float fsilu(float x) { return x * fsigmoid(x); }
; DI float dpp_ror1(float v) { return __int_as_float(__builtin_amdgcn_update_dpp(0, __float_as_int(v), 0x121, 0xf, 0xf, false)); }
; DI float dpp_ror2(float v) { return __int_as_float(__builtin_amdgcn_update_dpp(0, __float_as_int(v), 0x122, 0xf, 0xf, false)); }
;     DI void operator()(const f32x4 (&acc)[2][2][4][2], const pg8::Unit& u, int wr, int wcv, int fr, int fq) const {
;     ...
;             for (int m = 0; m < 4; ++m) {
;                 const int lrow = 64 * blk + 16 * m + fr, t = 254 * u.pm - 2 + lrow, spos = t & 2047;
;                 float o[8], r1[8], r2[8];
; #pragma unroll
;                 for (int e = 0; e < 8; ++e) { const float uc = acc[ai][0][m][e >> 2][e & 3], gv = acc[ai][1][m][e >> 2][e & 3];
;                     r1[e] = dpp_ror1(uc); r2[e] = dpp_ror2(uc);
;                     float um1 = (fr >= 1) ? r1[e] : p1[e], um2 = (fr >= 2) ? r2[e] : p2[e];
;                     if (spos < 1) um1 = 0.f;
;                     if (spos < 2) um2 = 0.f;
;                     const float v = bb[e] + w0[e] * um2 + w1[e] * um1 + w2[e] * uc;
;                     o[e] = fsilu(v) * gv; }
; #pragma unroll
;                 for (int e = 0; e < 8; ++e) { p1[e] = r1[e]; p2[e] = r2[e]; }
;                 if (lrow >= 2 && t < T) *(u32x4*)(act + (size_t)t * DFF + ch0) = pack8(o);
.LBB0_885:
	s_or_b64 exec, exec, s[58:59]
	v_add_u32_e32 v160, s53, v183
	v_mov_b32_e32 v159, v197
	v_mov_b32_e32 v158, v197
	v_mov_b32_e32 v157, v197
	v_mov_b32_e32 v156, v197
	v_mov_b32_e32 v155, v197
	v_mov_b32_e32 v154, v197
	v_mov_b32_e32 v153, v197
	v_mov_b32_e32 v152, v197
	v_mov_b32_e32 v151, v197
	v_mov_b32_e32 v150, v197
	v_mov_b32_e32 v149, v197
	v_mov_b32_e32 v148, v197
	v_mov_b32_e32 v147, v197
	v_mov_b32_e32 v146, v197
	v_mov_b32_e32 v145, v197
	v_mov_b32_e32 v144, v197
	v_cmp_gt_i32_e32 vcc, s19, v160
	v_mov_b32_dpp v159, v140 row_ror:1 row_mask:0xf bank_mask:0xf
	v_mov_b32_dpp v158, v140 row_ror:2 row_mask:0xf bank_mask:0xf
	v_mov_b32_dpp v157, v141 row_ror:1 row_mask:0xf bank_mask:0xf
	v_mov_b32_dpp v156, v141 row_ror:2 row_mask:0xf bank_mask:0xf
	v_mov_b32_dpp v155, v142 row_ror:1 row_mask:0xf bank_mask:0xf
	v_mov_b32_dpp v154, v142 row_ror:2 row_mask:0xf bank_mask:0xf
	v_mov_b32_dpp v153, v143 row_ror:1 row_mask:0xf bank_mask:0xf
	v_mov_b32_dpp v152, v143 row_ror:2 row_mask:0xf bank_mask:0xf
	v_mov_b32_dpp v151, v132 row_ror:1 row_mask:0xf bank_mask:0xf
	v_mov_b32_dpp v150, v132 row_ror:2 row_mask:0xf bank_mask:0xf
	v_mov_b32_dpp v149, v133 row_ror:1 row_mask:0xf bank_mask:0xf
	v_mov_b32_dpp v148, v133 row_ror:2 row_mask:0xf bank_mask:0xf
	v_mov_b32_dpp v147, v134 row_ror:1 row_mask:0xf bank_mask:0xf
	v_mov_b32_dpp v146, v134 row_ror:2 row_mask:0xf bank_mask:0xf
	v_mov_b32_dpp v145, v135 row_ror:1 row_mask:0xf bank_mask:0xf
	v_mov_b32_dpp v144, v135 row_ror:2 row_mask:0xf bank_mask:0xf
	s_and_b64 s[50:51], s[24:25], vcc
	s_and_saveexec_b64 s[58:59], s[50:51]
	s_cbranch_execz .LBB0_887
	v_and_b32_e32 v161, 0x7ff, v160
	v_cndmask_b32_e64 v162, v159, v235, s[40:41]
	v_cmp_eq_u32_e32 vcc, 0, v161
	v_mov_b32_e32 v164, v140
	v_cndmask_b32_e64 v140, v234, v158, s[42:43]
	v_cmp_gt_u32_e64 s[50:51], 2, v161
	v_cndmask_b32_e64 v163, v162, 0, vcc
	v_mov_b32_e32 v165, v84
	v_mov_b32_e32 v162, v88
	v_cndmask_b32_e64 v140, v140, 0, s[50:51]
	v_pk_mul_f32 v[162:163], v[164:165], v[162:163]
	v_fma_f32 v140, v80, v140, v92
	v_add_f32_e32 v140, v163, v140
	v_add_f32_e32 v161, v162, v140
	v_mul_f32_e32 v140, 0xbfb8aa3b, v161
	v_exp_f32_e32 v164, v140
	v_cndmask_b32_e64 v140, v157, v232, s[40:41]
	v_cndmask_b32_e64 v163, v140, 0, vcc
	v_mov_b32_e32 v140, v141
	v_mov_b32_e32 v141, v85
	v_mov_b32_e32 v162, v89
	v_pk_mul_f32 v[140:141], v[140:141], v[162:163]
	v_cndmask_b32_e64 v162, v223, v156, s[42:43]
	v_cndmask_b32_e64 v162, v162, 0, s[50:51]
	v_fma_f32 v162, v81, v162, v93
	v_add_f32_e32 v141, v141, v162
	v_add_f32_e32 v140, v140, v141
	v_mul_f32_e32 v141, 0xbfb8aa3b, v140
	v_exp_f32_e32 v141, v141
	v_add_f32_e32 v162, 1.0, v164
	v_rcp_f32_e32 v162, v162
	v_mov_b32_e32 v163, v86
	v_add_f32_e32 v141, 1.0, v141
	v_rcp_f32_e32 v141, v141
	v_mul_f32_e32 v161, v161, v162
	v_mul_f32_e32 v161, v136, v161
	v_mov_b32_e32 v162, v142
	v_mul_f32_e32 v136, v140, v141
	v_cndmask_b32_e64 v140, v155, v222, s[40:41]
	v_cndmask_b32_e64 v142, v221, v154, s[42:43]
	v_cndmask_b32_e64 v141, v140, 0, vcc
	v_mov_b32_e32 v140, v90
	v_cndmask_b32_e64 v142, v142, 0, s[50:51]
	v_pk_mul_f32 v[140:141], v[162:163], v[140:141]
	v_fma_f32 v142, v82, v142, v94
	v_add_f32_e32 v141, v141, v142
	v_add_f32_e32 v162, v140, v141
	v_mul_f32_e32 v140, 0xbfb8aa3b, v162
	v_exp_f32_e32 v163, v140
	v_cndmask_b32_e64 v140, v153, v220, s[40:41]
	v_cndmask_b32_e64 v141, v140, 0, vcc
	v_mov_b32_e32 v142, v143
	v_mov_b32_e32 v143, v87
	v_mov_b32_e32 v140, v91
	v_pk_mul_f32 v[140:141], v[142:143], v[140:141]
	v_cndmask_b32_e64 v142, v219, v152, s[42:43]
	v_cndmask_b32_e64 v142, v142, 0, s[50:51]
	v_fma_f32 v142, v83, v142, v95
	v_add_f32_e32 v141, v141, v142
	v_add_f32_e32 v142, v140, v141
	v_mul_f32_e32 v140, 0xbfb8aa3b, v142
	v_exp_f32_e32 v140, v140
	v_mul_f32_e32 v143, v137, v136
	v_add_f32_e32 v136, 1.0, v163
	v_rcp_f32_e32 v163, v136
	v_add_f32_e32 v136, 1.0, v140
	v_rcp_f32_e32 v164, v136
	v_cndmask_b32_e64 v136, v151, v218, s[40:41]
	v_mov_b32_e32 v140, v132
	v_cndmask_b32_e64 v132, v217, v150, s[42:43]
	v_cndmask_b32_e64 v137, v136, 0, vcc
	v_mov_b32_e32 v141, v64
	v_mov_b32_e32 v136, v68
	v_cndmask_b32_e64 v132, v132, 0, s[50:51]
	v_pk_mul_f32 v[136:137], v[140:141], v[136:137]
	v_fma_f32 v132, v60, v132, v72
	v_add_f32_e32 v132, v137, v132
	v_add_f32_e32 v140, v136, v132
	v_mul_f32_e32 v132, 0xbfb8aa3b, v140
	v_exp_f32_e32 v132, v132
	v_mul_f32_e32 v136, v162, v163
	v_mul_f32_e32 v141, v142, v164
	v_mul_f32_e32 v138, v138, v136
	v_add_f32_e32 v132, 1.0, v132
	v_rcp_f32_e32 v142, v132
	v_cndmask_b32_e64 v132, v149, v216, s[40:41]
	v_cndmask_b32_e64 v137, v132, 0, vcc
	v_mov_b32_e32 v132, v133
	v_mov_b32_e32 v133, v65
	v_mov_b32_e32 v136, v69
	v_pk_mul_f32 v[132:133], v[132:133], v[136:137]
	v_cndmask_b32_e64 v136, v215, v148, s[42:43]
	v_cndmask_b32_e64 v136, v136, 0, s[50:51]
	v_fma_f32 v136, v61, v136, v73
	v_add_f32_e32 v133, v133, v136
	v_add_f32_e32 v162, v132, v133
	v_mul_f32_e32 v132, 0xbfb8aa3b, v162
	v_exp_f32_e32 v132, v132
	v_mul_f32_e32 v133, v140, v142
	v_mul_f32_e32 v140, v128, v133
	v_mov_b32_e32 v136, v134
	v_add_f32_e32 v128, 1.0, v132
	v_cndmask_b32_e64 v132, v147, v214, s[40:41]
	v_cndmask_b32_e64 v134, v213, v146, s[42:43]
	v_cndmask_b32_e64 v133, v132, 0, vcc
	v_mov_b32_e32 v137, v66
	v_mov_b32_e32 v132, v70
	v_cndmask_b32_e64 v134, v134, 0, s[50:51]
	v_pk_mul_f32 v[132:133], v[136:137], v[132:133]
	v_fma_f32 v134, v62, v134, v74
	v_add_f32_e32 v133, v133, v134
	v_add_f32_e32 v136, v132, v133
	v_mul_f32_e32 v132, 0xbfb8aa3b, v136
	v_exp_f32_e32 v137, v132
	v_cndmask_b32_e64 v132, v145, v212, s[40:41]
	v_cndmask_b32_e64 v133, v132, 0, vcc
	v_mov_b32_e32 v134, v135
	v_mov_b32_e32 v135, v67
	v_mov_b32_e32 v132, v71
	v_pk_mul_f32 v[132:133], v[134:135], v[132:133]
	v_cndmask_b32_e64 v134, v195, v144, s[42:43]
	v_cndmask_b32_e64 v134, v134, 0, s[50:51]
	v_fma_f32 v134, v63, v134, v75
	v_add_f32_e32 v133, v133, v134
	v_add_f32_e32 v132, v132, v133
	v_mul_f32_e32 v133, 0xbfb8aa3b, v132
	v_exp_f32_e32 v133, v133
	v_rcp_f32_e32 v128, v128
	v_add_f32_e32 v134, 1.0, v137
	v_rcp_f32_e32 v134, v134
	v_add_f32_e32 v133, 1.0, v133
	v_rcp_f32_e32 v133, v133
	v_mul_f32_e32 v128, v162, v128
	v_mul_f32_e32 v135, v129, v128
	v_mul_f32_e32 v128, v136, v134
	v_mul_f32_e32 v134, v130, v128
	v_mul_f32_e32 v128, v132, v133
	v_mov_b64_e32 v[132:133], s[4:5]
	s_movk_i32 s50, 0x1600
	v_mul_f32_e32 v139, v139, v141
	v_mul_f32_e32 v131, v131, v128
	v_mad_i64_i32 v[132:133], s[50:51], v160, s50, v[132:133]
	v_cvt_pk_bf16_f32 v128, v161, v143
	v_cvt_pk_bf16_f32 v129, v138, v139
	v_cvt_pk_bf16_f32 v130, v140, v135
	v_cvt_pk_bf16_f32 v131, v134, v131
	v_lshl_add_u64 v[132:133], v[178:179], 1, v[132:133]
	global_store_dwordx4 v[132:133], v[128:131], off
; DI u32x4 pack8(const float (&f)[8]) { u32x4 w; w.x = pk2(f[0], f[1]); w.y = pk2(f[2], f[3]); w.z = pk2(f[4], f[5]); w.w = pk2(f[6], f[7]); return w; }
; DI float fsilu(float x) { return x * fsigmoid(x); }
; DI float dpp_ror1(float v) { return __int_as_float(__builtin_amdgcn_update_dpp(0, __float_as_int(v), 0x121, 0xf, 0xf, false)); }
; DI float dpp_ror2(float v) { return __int_as_float(__builtin_amdgcn_update_dpp(0, __float_as_int(v), 0x122, 0xf, 0xf, false)); }
;     DI void operator()(const f32x4 (&acc)[2][2][4][2], const pg8::Unit& u, int wr, int wcv, int fr, int fq) const {
;     ...
;             for (int m = 0; m < 4; ++m) {
;                 const int lrow = 64 * blk + 16 * m + fr, t = 254 * u.pm - 2 + lrow, spos = t & 2047;
;                 float o[8], r1[8], r2[8];
; #pragma unroll
;                 for (int e = 0; e < 8; ++e) { const float uc = acc[ai][0][m][e >> 2][e & 3], gv = acc[ai][1][m][e >> 2][e & 3];
;                     r1[e] = dpp_ror1(uc); r2[e] = dpp_ror2(uc);
;                     float um1 = (fr >= 1) ? r1[e] : p1[e], um2 = (fr >= 2) ? r2[e] : p2[e];
;                     if (spos < 1) um1 = 0.f;
;                     if (spos < 2) um2 = 0.f;
;                     const float v = bb[e] + w0[e] * um2 + w1[e] * um1 + w2[e] * uc;
;                     o[e] = fsilu(v) * gv; }
; #pragma unroll
;                 for (int e = 0; e < 8; ++e) { p1[e] = r1[e]; p2[e] = r2[e]; }
;                 if (lrow >= 2 && t < T) *(u32x4*)(act + (size_t)t * DFF + ch0) = pack8(o);
.LBB0_887:
	s_or_b64 exec, exec, s[58:59]
	v_add_u32_e32 v160, s53, v184
	v_mov_b32_e32 v143, v197
	v_mov_b32_e32 v142, v197
	v_mov_b32_e32 v141, v197
	v_mov_b32_e32 v140, v197
	v_mov_b32_e32 v139, v197
	v_mov_b32_e32 v138, v197
	v_mov_b32_e32 v137, v197
	v_mov_b32_e32 v136, v197
	v_mov_b32_e32 v135, v197
	v_mov_b32_e32 v134, v197
	v_mov_b32_e32 v133, v197
	v_mov_b32_e32 v132, v197
	v_mov_b32_e32 v131, v197
	v_mov_b32_e32 v130, v197
	v_mov_b32_e32 v129, v197
	v_mov_b32_e32 v128, v197
	v_cmp_gt_i32_e32 vcc, s19, v160
	v_mov_b32_dpp v143, v124 row_ror:1 row_mask:0xf bank_mask:0xf
	v_mov_b32_dpp v142, v124 row_ror:2 row_mask:0xf bank_mask:0xf
	v_mov_b32_dpp v141, v125 row_ror:1 row_mask:0xf bank_mask:0xf
	v_mov_b32_dpp v140, v125 row_ror:2 row_mask:0xf bank_mask:0xf
	v_mov_b32_dpp v139, v126 row_ror:1 row_mask:0xf bank_mask:0xf
	v_mov_b32_dpp v138, v126 row_ror:2 row_mask:0xf bank_mask:0xf
	v_mov_b32_dpp v137, v127 row_ror:1 row_mask:0xf bank_mask:0xf
	v_mov_b32_dpp v136, v127 row_ror:2 row_mask:0xf bank_mask:0xf
	v_mov_b32_dpp v135, v116 row_ror:1 row_mask:0xf bank_mask:0xf
	v_mov_b32_dpp v134, v116 row_ror:2 row_mask:0xf bank_mask:0xf
	v_mov_b32_dpp v133, v117 row_ror:1 row_mask:0xf bank_mask:0xf
	v_mov_b32_dpp v132, v117 row_ror:2 row_mask:0xf bank_mask:0xf
	v_mov_b32_dpp v131, v118 row_ror:1 row_mask:0xf bank_mask:0xf
	v_mov_b32_dpp v130, v118 row_ror:2 row_mask:0xf bank_mask:0xf
	v_mov_b32_dpp v129, v119 row_ror:1 row_mask:0xf bank_mask:0xf
	v_mov_b32_dpp v128, v119 row_ror:2 row_mask:0xf bank_mask:0xf
	s_and_b64 s[50:51], s[24:25], vcc
	s_and_saveexec_b64 s[58:59], s[50:51]
	s_cbranch_execz .LBB0_889
	v_and_b32_e32 v161, 0x7ff, v160
	v_cndmask_b32_e64 v159, v143, v159, s[40:41]
	v_cmp_eq_u32_e32 vcc, 0, v161
	v_mov_b32_e32 v164, v124
	v_cndmask_b32_e64 v124, v158, v142, s[42:43]
	v_cmp_gt_u32_e64 s[50:51], 2, v161
	v_cndmask_b32_e64 v163, v159, 0, vcc
	v_mov_b32_e32 v165, v84
	v_mov_b32_e32 v162, v88
	v_cndmask_b32_e64 v124, v124, 0, s[50:51]
	v_pk_mul_f32 v[162:163], v[164:165], v[162:163]
	v_fma_f32 v124, v80, v124, v92
	v_add_f32_e32 v124, v163, v124
	v_add_f32_e32 v161, v162, v124
	v_mul_f32_e32 v124, 0xbfb8aa3b, v161
	v_exp_f32_e32 v162, v124
	v_cndmask_b32_e64 v124, v141, v157, s[40:41]
	v_cndmask_b32_e64 v156, v156, v140, s[42:43]
	v_cndmask_b32_e64 v159, v124, 0, vcc
	v_mov_b32_e32 v124, v125
	v_mov_b32_e32 v125, v85
	v_mov_b32_e32 v158, v89
	v_cndmask_b32_e64 v156, v156, 0, s[50:51]
	v_pk_mul_f32 v[124:125], v[124:125], v[158:159]
	v_fma_f32 v156, v81, v156, v93
	v_add_f32_e32 v125, v125, v156
	v_add_f32_e32 v124, v124, v125
	v_mul_f32_e32 v125, 0xbfb8aa3b, v124
	v_exp_f32_e32 v125, v125
	v_add_f32_e32 v156, 1.0, v162
	v_rcp_f32_e32 v156, v156
	v_mov_b32_e32 v157, v86
	v_add_f32_e32 v125, 1.0, v125
	v_rcp_f32_e32 v125, v125
	v_mul_f32_e32 v156, v161, v156
	v_mul_f32_e32 v158, v120, v156
	v_mov_b32_e32 v156, v126
	v_mul_f32_e32 v120, v124, v125
	v_cndmask_b32_e64 v124, v139, v155, s[40:41]
	v_cndmask_b32_e64 v126, v154, v138, s[42:43]
	v_cndmask_b32_e64 v125, v124, 0, vcc
	v_mov_b32_e32 v124, v90
	v_cndmask_b32_e64 v126, v126, 0, s[50:51]
	v_pk_mul_f32 v[124:125], v[156:157], v[124:125]
	v_fma_f32 v126, v82, v126, v94
	v_add_f32_e32 v125, v125, v126
	v_add_f32_e32 v154, v124, v125
	v_mul_f32_e32 v124, 0xbfb8aa3b, v154
	v_exp_f32_e32 v155, v124
	v_cndmask_b32_e64 v124, v137, v153, s[40:41]
	v_cndmask_b32_e64 v125, v124, 0, vcc
	v_mov_b32_e32 v126, v127
	v_mov_b32_e32 v127, v87
	v_mov_b32_e32 v124, v91
	v_pk_mul_f32 v[124:125], v[126:127], v[124:125]
	v_cndmask_b32_e64 v126, v152, v136, s[42:43]
	v_cndmask_b32_e64 v126, v126, 0, s[50:51]
	v_fma_f32 v126, v83, v126, v95
	v_add_f32_e32 v125, v125, v126
	v_add_f32_e32 v126, v124, v125
	v_mul_f32_e32 v124, 0xbfb8aa3b, v126
	v_exp_f32_e32 v124, v124
	v_mul_f32_e32 v127, v121, v120
	v_add_f32_e32 v120, 1.0, v155
	v_rcp_f32_e32 v152, v120
	v_add_f32_e32 v120, 1.0, v124
	v_rcp_f32_e32 v153, v120
	v_cndmask_b32_e64 v120, v135, v151, s[40:41]
	v_mov_b32_e32 v124, v116
	v_cndmask_b32_e64 v116, v150, v134, s[42:43]
	v_cndmask_b32_e64 v121, v120, 0, vcc
	v_mov_b32_e32 v125, v64
	v_mov_b32_e32 v120, v68
	v_cndmask_b32_e64 v116, v116, 0, s[50:51]
	v_pk_mul_f32 v[120:121], v[124:125], v[120:121]
	v_fma_f32 v116, v60, v116, v72
	v_add_f32_e32 v116, v121, v116
	v_add_f32_e32 v124, v120, v116
	v_mul_f32_e32 v116, 0xbfb8aa3b, v124
	v_exp_f32_e32 v116, v116
	v_mul_f32_e32 v120, v154, v152
	v_mul_f32_e32 v125, v126, v153
	v_mul_f32_e32 v122, v122, v120
	v_add_f32_e32 v116, 1.0, v116
	v_rcp_f32_e32 v126, v116
	v_cndmask_b32_e64 v116, v133, v149, s[40:41]
	v_cndmask_b32_e64 v121, v116, 0, vcc
	v_mov_b32_e32 v116, v117
	v_mov_b32_e32 v117, v65
	v_mov_b32_e32 v120, v69
	v_pk_mul_f32 v[116:117], v[116:117], v[120:121]
	v_cndmask_b32_e64 v120, v148, v132, s[42:43]
	v_cndmask_b32_e64 v120, v120, 0, s[50:51]
	v_fma_f32 v120, v61, v120, v73
	v_add_f32_e32 v117, v117, v120
	v_add_f32_e32 v148, v116, v117
	v_mul_f32_e32 v116, 0xbfb8aa3b, v148
	v_exp_f32_e32 v116, v116
	v_mul_f32_e32 v117, v124, v126
	v_mul_f32_e32 v124, v112, v117
	v_mov_b32_e32 v120, v118
	v_add_f32_e32 v112, 1.0, v116
	v_cndmask_b32_e64 v116, v131, v147, s[40:41]
	v_cndmask_b32_e64 v118, v146, v130, s[42:43]
	v_cndmask_b32_e64 v117, v116, 0, vcc
	v_mov_b32_e32 v121, v66
	v_mov_b32_e32 v116, v70
	v_cndmask_b32_e64 v118, v118, 0, s[50:51]
	v_pk_mul_f32 v[116:117], v[120:121], v[116:117]
	v_fma_f32 v118, v62, v118, v74
	v_add_f32_e32 v117, v117, v118
	v_add_f32_e32 v120, v116, v117
	v_mul_f32_e32 v116, 0xbfb8aa3b, v120
	v_exp_f32_e32 v121, v116
	v_cndmask_b32_e64 v116, v129, v145, s[40:41]
	v_cndmask_b32_e64 v117, v116, 0, vcc
	v_mov_b32_e32 v118, v119
	v_mov_b32_e32 v119, v67
	v_mov_b32_e32 v116, v71
	v_pk_mul_f32 v[116:117], v[118:119], v[116:117]
	v_cndmask_b32_e64 v118, v144, v128, s[42:43]
	v_cndmask_b32_e64 v118, v118, 0, s[50:51]
	v_fma_f32 v118, v63, v118, v75
	v_add_f32_e32 v117, v117, v118
	v_add_f32_e32 v116, v116, v117
	v_mul_f32_e32 v117, 0xbfb8aa3b, v116
	v_exp_f32_e32 v117, v117
	v_rcp_f32_e32 v112, v112
	v_add_f32_e32 v118, 1.0, v121
	v_rcp_f32_e32 v118, v118
	v_add_f32_e32 v117, 1.0, v117
	v_rcp_f32_e32 v117, v117
	v_mul_f32_e32 v112, v148, v112
	v_mul_f32_e32 v119, v113, v112
	v_mul_f32_e32 v112, v120, v118
	v_mul_f32_e32 v118, v114, v112
	v_mul_f32_e32 v112, v116, v117
	v_mov_b64_e32 v[116:117], s[4:5]
	s_movk_i32 s50, 0x1600
	v_mul_f32_e32 v123, v123, v125
	v_mul_f32_e32 v115, v115, v112
	v_mad_i64_i32 v[116:117], s[50:51], v160, s50, v[116:117]
	v_cvt_pk_bf16_f32 v112, v158, v127
	v_cvt_pk_bf16_f32 v113, v122, v123
	v_cvt_pk_bf16_f32 v114, v124, v119
	v_cvt_pk_bf16_f32 v115, v118, v115
	v_lshl_add_u64 v[116:117], v[178:179], 1, v[116:117]
	global_store_dwordx4 v[116:117], v[112:115], off
; DI u32x4 pack8(const float (&f)[8]) { u32x4 w; w.x = pk2(f[0], f[1]); w.y = pk2(f[2], f[3]); w.z = pk2(f[4], f[5]); w.w = pk2(f[6], f[7]); return w; }
; DI float fsilu(float x) { return x * fsigmoid(x); }
; DI float dpp_ror1(float v) { return __int_as_float(__builtin_amdgcn_update_dpp(0, __float_as_int(v), 0x121, 0xf, 0xf, false)); }
; DI float dpp_ror2(float v) { return __int_as_float(__builtin_amdgcn_update_dpp(0, __float_as_int(v), 0x122, 0xf, 0xf, false)); }
;     DI void operator()(const f32x4 (&acc)[2][2][4][2], const pg8::Unit& u, int wr, int wcv, int fr, int fq) const {
;     ...
;             for (int m = 0; m < 4; ++m) {
;                 const int lrow = 64 * blk + 16 * m + fr, t = 254 * u.pm - 2 + lrow, spos = t & 2047;
;                 float o[8], r1[8], r2[8];
; #pragma unroll
;                 for (int e = 0; e < 8; ++e) { const float uc = acc[ai][0][m][e >> 2][e & 3], gv = acc[ai][1][m][e >> 2][e & 3];
;                     r1[e] = dpp_ror1(uc); r2[e] = dpp_ror2(uc);
;                     float um1 = (fr >= 1) ? r1[e] : p1[e], um2 = (fr >= 2) ? r2[e] : p2[e];
;                     if (spos < 1) um1 = 0.f;
;                     if (spos < 2) um2 = 0.f;
;                     const float v = bb[e] + w0[e] * um2 + w1[e] * um1 + w2[e] * uc;
;                     o[e] = fsilu(v) * gv; }
; #pragma unroll
;                 for (int e = 0; e < 8; ++e) { p1[e] = r1[e]; p2[e] = r2[e]; }
;                 if (lrow >= 2 && t < T) *(u32x4*)(act + (size_t)t * DFF + ch0) = pack8(o);
.LBB0_889:
	s_or_b64 exec, exec, s[58:59]
	s_nop 0
	v_add_u32_e32 v112, s53, v185
	v_mov_b32_e32 v144, v197
	v_mov_b32_e32 v127, v197
	v_mov_b32_e32 v126, v197
	v_mov_b32_e32 v125, v197
	v_mov_b32_e32 v124, v197
	v_mov_b32_e32 v123, v197
	v_mov_b32_e32 v122, v197
	v_mov_b32_e32 v121, v197
	v_mov_b32_e32 v120, v197
	v_mov_b32_e32 v119, v197
	v_mov_b32_e32 v118, v197
	v_mov_b32_e32 v117, v197
	v_mov_b32_e32 v116, v197
	v_mov_b32_e32 v115, v197
	v_mov_b32_e32 v114, v197
	v_mov_b32_e32 v113, v197
	v_cmp_gt_i32_e32 vcc, s19, v112
	v_mov_b32_dpp v144, v108 row_ror:1 row_mask:0xf bank_mask:0xf
	v_mov_b32_dpp v127, v108 row_ror:2 row_mask:0xf bank_mask:0xf
	v_mov_b32_dpp v126, v109 row_ror:1 row_mask:0xf bank_mask:0xf
	v_mov_b32_dpp v125, v109 row_ror:2 row_mask:0xf bank_mask:0xf
	v_mov_b32_dpp v124, v110 row_ror:1 row_mask:0xf bank_mask:0xf
	v_mov_b32_dpp v123, v110 row_ror:2 row_mask:0xf bank_mask:0xf
	v_mov_b32_dpp v122, v111 row_ror:1 row_mask:0xf bank_mask:0xf
	v_mov_b32_dpp v121, v111 row_ror:2 row_mask:0xf bank_mask:0xf
	v_mov_b32_dpp v120, v100 row_ror:1 row_mask:0xf bank_mask:0xf
	v_mov_b32_dpp v119, v100 row_ror:2 row_mask:0xf bank_mask:0xf
	v_mov_b32_dpp v118, v101 row_ror:1 row_mask:0xf bank_mask:0xf
	v_mov_b32_dpp v117, v101 row_ror:2 row_mask:0xf bank_mask:0xf
	v_mov_b32_dpp v116, v102 row_ror:1 row_mask:0xf bank_mask:0xf
	v_mov_b32_dpp v115, v102 row_ror:2 row_mask:0xf bank_mask:0xf
	v_mov_b32_dpp v114, v103 row_ror:1 row_mask:0xf bank_mask:0xf
	v_mov_b32_dpp v113, v103 row_ror:2 row_mask:0xf bank_mask:0xf
	s_and_b64 s[50:51], s[24:25], vcc
	s_and_saveexec_b64 s[58:59], s[50:51]
	s_cbranch_execz .LBB0_891
	v_and_b32_e32 v148, 0x7ff, v112
	v_cndmask_b32_e64 v143, v144, v143, s[40:41]
	v_cmp_eq_u32_e32 vcc, 0, v148
	v_mov_b32_e32 v146, v108
	v_cndmask_b32_e64 v108, v142, v127, s[42:43]
	v_cmp_gt_u32_e64 s[50:51], 2, v148
	v_cndmask_b32_e64 v145, v143, 0, vcc
	v_mov_b32_e32 v147, v84
	v_mov_b32_e32 v144, v88
	v_cndmask_b32_e64 v108, v108, 0, s[50:51]
	v_pk_mul_f32 v[144:145], v[146:147], v[144:145]
	v_fma_f32 v108, v80, v108, v92
	v_add_f32_e32 v108, v145, v108
	v_add_f32_e32 v142, v144, v108
	v_mul_f32_e32 v108, 0xbfb8aa3b, v142
	v_exp_f32_e32 v143, v108
	v_cndmask_b32_e64 v108, v126, v141, s[40:41]
	v_cndmask_b32_e64 v125, v140, v125, s[42:43]
	v_cndmask_b32_e64 v127, v108, 0, vcc
	v_mov_b32_e32 v108, v109
	v_mov_b32_e32 v109, v85
	v_mov_b32_e32 v126, v89
	v_cndmask_b32_e64 v125, v125, 0, s[50:51]
	v_pk_mul_f32 v[108:109], v[108:109], v[126:127]
	v_fma_f32 v125, v81, v125, v93
	v_add_f32_e32 v109, v109, v125
	v_add_f32_e32 v108, v108, v109
	v_mul_f32_e32 v109, 0xbfb8aa3b, v108
	v_exp_f32_e32 v109, v109
	v_add_f32_e32 v125, 1.0, v143
	v_rcp_f32_e32 v125, v125
	v_add_f32_e32 v109, 1.0, v109
	v_rcp_f32_e32 v109, v109
	v_mul_f32_e32 v125, v142, v125
	v_mul_f32_e32 v126, v104, v125
	v_mov_b32_e32 v125, v86
	v_mul_f32_e32 v104, v108, v109
	v_cndmask_b32_e64 v108, v124, v139, s[40:41]
	v_mov_b32_e32 v124, v110
	v_cndmask_b32_e64 v110, v138, v123, s[42:43]
	v_cndmask_b32_e64 v109, v108, 0, vcc
	v_mov_b32_e32 v108, v90
	v_cndmask_b32_e64 v110, v110, 0, s[50:51]
	v_pk_mul_f32 v[108:109], v[124:125], v[108:109]
	v_fma_f32 v110, v82, v110, v94
	v_add_f32_e32 v109, v109, v110
	v_add_f32_e32 v123, v108, v109
	v_mul_f32_e32 v108, 0xbfb8aa3b, v123
	v_exp_f32_e32 v124, v108
	v_cndmask_b32_e64 v108, v122, v137, s[40:41]
	v_cndmask_b32_e64 v109, v108, 0, vcc
	v_mov_b32_e32 v110, v111
	v_mov_b32_e32 v111, v87
	v_mov_b32_e32 v108, v91
	v_pk_mul_f32 v[108:109], v[110:111], v[108:109]
	v_cndmask_b32_e64 v110, v136, v121, s[42:43]
	v_cndmask_b32_e64 v110, v110, 0, s[50:51]
	v_fma_f32 v110, v83, v110, v95
	v_add_f32_e32 v109, v109, v110
	v_add_f32_e32 v110, v108, v109
	v_mul_f32_e32 v108, 0xbfb8aa3b, v110
	v_exp_f32_e32 v108, v108
	v_mul_f32_e32 v111, v105, v104
	v_add_f32_e32 v104, 1.0, v124
	v_rcp_f32_e32 v121, v104
	v_add_f32_e32 v104, 1.0, v108
	v_rcp_f32_e32 v122, v104
	v_cndmask_b32_e64 v104, v120, v135, s[40:41]
	v_mov_b32_e32 v108, v100
	v_cndmask_b32_e64 v100, v134, v119, s[42:43]
	v_cndmask_b32_e64 v105, v104, 0, vcc
	v_mov_b32_e32 v109, v64
	v_mov_b32_e32 v104, v68
	v_cndmask_b32_e64 v100, v100, 0, s[50:51]
	v_pk_mul_f32 v[104:105], v[108:109], v[104:105]
	v_fma_f32 v100, v60, v100, v72
	v_add_f32_e32 v100, v105, v100
	v_add_f32_e32 v108, v104, v100
	v_mul_f32_e32 v100, 0xbfb8aa3b, v108
	v_exp_f32_e32 v100, v100
	v_mul_f32_e32 v104, v123, v121
	v_mul_f32_e32 v109, v110, v122
	v_mul_f32_e32 v106, v106, v104
	v_add_f32_e32 v100, 1.0, v100
	v_rcp_f32_e32 v110, v100
	v_cndmask_b32_e64 v100, v118, v133, s[40:41]
	v_cndmask_b32_e64 v105, v100, 0, vcc
	v_mov_b32_e32 v100, v101
	v_mov_b32_e32 v101, v65
	v_mov_b32_e32 v104, v69
	v_pk_mul_f32 v[100:101], v[100:101], v[104:105]
	v_cndmask_b32_e64 v104, v132, v117, s[42:43]
	v_cndmask_b32_e64 v104, v104, 0, s[50:51]
	v_fma_f32 v104, v61, v104, v73
	v_add_f32_e32 v101, v101, v104
	v_add_f32_e32 v117, v100, v101
	v_mul_f32_e32 v100, 0xbfb8aa3b, v117
	v_exp_f32_e32 v100, v100
	v_mul_f32_e32 v101, v108, v110
	v_mul_f32_e32 v108, v96, v101
	v_mov_b32_e32 v104, v102
	v_add_f32_e32 v96, 1.0, v100
	v_cndmask_b32_e64 v100, v116, v131, s[40:41]
	v_cndmask_b32_e64 v102, v130, v115, s[42:43]
	v_cndmask_b32_e64 v101, v100, 0, vcc
	v_mov_b32_e32 v105, v66
	v_mov_b32_e32 v100, v70
	v_cndmask_b32_e64 v102, v102, 0, s[50:51]
	v_pk_mul_f32 v[100:101], v[104:105], v[100:101]
	v_fma_f32 v102, v62, v102, v74
	v_add_f32_e32 v101, v101, v102
	v_add_f32_e32 v104, v100, v101
	v_mul_f32_e32 v100, 0xbfb8aa3b, v104
	v_exp_f32_e32 v105, v100
	v_cndmask_b32_e64 v100, v114, v129, s[40:41]
	v_cndmask_b32_e64 v101, v100, 0, vcc
	v_mov_b32_e32 v102, v103
	v_mov_b32_e32 v103, v67
	v_mov_b32_e32 v100, v71
	v_pk_mul_f32 v[100:101], v[102:103], v[100:101]
	v_cndmask_b32_e64 v102, v128, v113, s[42:43]
	v_cndmask_b32_e64 v102, v102, 0, s[50:51]
	v_fma_f32 v102, v63, v102, v75
	v_add_f32_e32 v101, v101, v102
	v_add_f32_e32 v100, v100, v101
	v_mul_f32_e32 v101, 0xbfb8aa3b, v100
	v_exp_f32_e32 v101, v101
	v_rcp_f32_e32 v96, v96
	v_add_f32_e32 v102, 1.0, v105
	v_rcp_f32_e32 v102, v102
	v_add_f32_e32 v101, 1.0, v101
	v_rcp_f32_e32 v101, v101
	v_mul_f32_e32 v96, v117, v96
	v_mul_f32_e32 v103, v97, v96
	v_mul_f32_e32 v96, v104, v102
	v_mul_f32_e32 v102, v98, v96
	v_mul_f32_e32 v96, v100, v101
	v_mov_b64_e32 v[100:101], s[4:5]
	s_movk_i32 s50, 0x1600
	v_mul_f32_e32 v107, v107, v109
	v_mul_f32_e32 v99, v99, v96
	v_mad_i64_i32 v[100:101], s[50:51], v112, s50, v[100:101]
	v_cvt_pk_bf16_f32 v96, v126, v111
	v_cvt_pk_bf16_f32 v97, v106, v107
	v_cvt_pk_bf16_f32 v98, v108, v103
	v_cvt_pk_bf16_f32 v99, v102, v99
	v_lshl_add_u64 v[100:101], v[178:179], 1, v[100:101]
	global_store_dwordx4 v[100:101], v[96:99], off

; DI u32x4 pack8(const float (&f)[8]) { u32x4 w; w.x = pk2(f[0], f[1]); w.y = pk2(f[2], f[3]); w.z = pk2(f[4], f[5]); w.w = pk2(f[6], f[7]); return w; }
; DI float fsilu(float x) { return x * fsigmoid(x); }
; DI float dpp_ror1(float v) { return __int_as_float(__builtin_amdgcn_update_dpp(0, __float_as_int(v), 0x121, 0xf, 0xf, false)); }
; DI float dpp_ror2(float v) { return __int_as_float(__builtin_amdgcn_update_dpp(0, __float_as_int(v), 0x122, 0xf, 0xf, false)); }
;     DI void operator()(const f32x4 (&acc)[2][2][4][2], const pg8::Unit& u, int wr, int wcv, int fr, int fq) const {
;     ...
;             for (int m = 0; m < 4; ++m) {
;                 const int lrow = 64 * blk + 16 * m + fr, t = 254 * u.pm - 2 + lrow, spos = t & 2047;
;                 float o[8], r1[8], r2[8];
; #pragma unroll
;                 for (int e = 0; e < 8; ++e) { const float uc = acc[ai][0][m][e >> 2][e & 3], gv = acc[ai][1][m][e >> 2][e & 3];
;                     r1[e] = dpp_ror1(uc); r2[e] = dpp_ror2(uc);
;                     float um1 = (fr >= 1) ? r1[e] : p1[e], um2 = (fr >= 2) ? r2[e] : p2[e];
;                     if (spos < 1) um1 = 0.f;
;                     if (spos < 2) um2 = 0.f;
;                     const float v = bb[e] + w0[e] * um2 + w1[e] * um1 + w2[e] * uc;
;                     o[e] = fsilu(v) * gv; }
; #pragma unroll
;                 for (int e = 0; e < 8; ++e) { p1[e] = r1[e]; p2[e] = r2[e]; }
;                 if (lrow >= 2 && t < T) *(u32x4*)(act + (size_t)t * DFF + ch0) = pack8(o);
.LBB0_893:
	v_add_u32_e32 v122, s53, v186
	v_mov_b32_e32 v119, v197
	v_mov_b32_e32 v118, v197
	v_mov_b32_e32 v117, v197
	v_mov_b32_e32 v116, v197
	v_mov_b32_e32 v115, v197
	v_mov_b32_e32 v114, v197
	v_mov_b32_e32 v113, v197
	v_mov_b32_e32 v112, v197
	v_mov_b32_e32 v111, v197
	v_mov_b32_e32 v110, v197
	v_mov_b32_e32 v109, v197
	v_mov_b32_e32 v108, v197
	v_mov_b32_e32 v107, v197
	v_mov_b32_e32 v106, v197
	v_mov_b32_e32 v105, v197
	v_mov_b32_e32 v104, v197
	v_cmp_gt_i32_e32 vcc, s19, v122
	v_mov_b32_dpp v119, v76 row_ror:1 row_mask:0xf bank_mask:0xf
	v_mov_b32_dpp v118, v76 row_ror:2 row_mask:0xf bank_mask:0xf
	v_mov_b32_dpp v117, v77 row_ror:1 row_mask:0xf bank_mask:0xf
	v_mov_b32_dpp v116, v77 row_ror:2 row_mask:0xf bank_mask:0xf
	v_mov_b32_dpp v115, v78 row_ror:1 row_mask:0xf bank_mask:0xf
	v_mov_b32_dpp v114, v78 row_ror:2 row_mask:0xf bank_mask:0xf
	v_mov_b32_dpp v113, v79 row_ror:1 row_mask:0xf bank_mask:0xf
	v_mov_b32_dpp v112, v79 row_ror:2 row_mask:0xf bank_mask:0xf
	v_mov_b32_dpp v111, v52 row_ror:1 row_mask:0xf bank_mask:0xf
	v_mov_b32_dpp v110, v52 row_ror:2 row_mask:0xf bank_mask:0xf
	v_mov_b32_dpp v109, v53 row_ror:1 row_mask:0xf bank_mask:0xf
	v_mov_b32_dpp v108, v53 row_ror:2 row_mask:0xf bank_mask:0xf
	v_mov_b32_dpp v107, v54 row_ror:1 row_mask:0xf bank_mask:0xf
	v_mov_b32_dpp v106, v54 row_ror:2 row_mask:0xf bank_mask:0xf
	v_mov_b32_dpp v105, v55 row_ror:1 row_mask:0xf bank_mask:0xf
	v_mov_b32_dpp v104, v55 row_ror:2 row_mask:0xf bank_mask:0xf
	s_and_b64 s[50:51], s[46:47], vcc
	s_and_saveexec_b64 s[58:59], s[50:51]
	s_cbranch_execz .LBB0_895
	v_and_b32_e32 v129, 0x7ff, v122
	v_cndmask_b32_e64 v100, v119, v100, s[40:41]
	v_cmp_eq_u32_e32 vcc, 0, v129
	v_mov_b32_e32 v132, v76
	v_cndmask_b32_e64 v76, v128, v118, s[42:43]
	v_cmp_gt_u32_e64 s[50:51], 2, v129
	v_cndmask_b32_e64 v131, v100, 0, vcc
	v_mov_b32_e32 v133, v84
	v_mov_b32_e32 v130, v88
	v_cndmask_b32_e64 v76, v76, 0, s[50:51]
	v_pk_mul_f32 v[130:131], v[132:133], v[130:131]
	v_fma_f32 v76, v80, v76, v92
	v_add_f32_e32 v76, v131, v76
	v_add_f32_e32 v128, v130, v76
	v_mul_f32_e32 v76, 0xbfb8aa3b, v128
	v_exp_f32_e32 v129, v76
	v_cndmask_b32_e64 v76, v117, v101, s[40:41]
	v_cndmask_b32_e64 v101, v76, 0, vcc
	v_mov_b32_e32 v76, v77
	v_mov_b32_e32 v77, v85
	v_mov_b32_e32 v100, v89
	v_pk_mul_f32 v[76:77], v[76:77], v[100:101]
	v_cndmask_b32_e64 v100, v127, v116, s[42:43]
	v_cndmask_b32_e64 v100, v100, 0, s[50:51]
	v_fma_f32 v100, v81, v100, v93
	v_add_f32_e32 v77, v77, v100
	v_add_f32_e32 v76, v76, v77
	v_mul_f32_e32 v77, 0xbfb8aa3b, v76
	v_exp_f32_e32 v77, v77
	v_add_f32_e32 v100, 1.0, v129
	v_rcp_f32_e32 v100, v100
	v_mov_b32_e32 v101, v86
	v_add_f32_e32 v77, 1.0, v77
	v_rcp_f32_e32 v77, v77
	v_mul_f32_e32 v100, v128, v100
	v_mul_f32_e32 v127, v56, v100
	v_mov_b32_e32 v100, v78
	v_mul_f32_e32 v56, v76, v77
	v_cndmask_b32_e64 v76, v115, v102, s[40:41]
	v_cndmask_b32_e64 v78, v125, v114, s[42:43]
	v_cndmask_b32_e64 v77, v76, 0, vcc
	v_mov_b32_e32 v76, v90
	v_cndmask_b32_e64 v78, v78, 0, s[50:51]
	v_pk_mul_f32 v[76:77], v[100:101], v[76:77]
	v_fma_f32 v78, v82, v78, v94
	v_add_f32_e32 v77, v77, v78
	v_add_f32_e32 v100, v76, v77
	v_mul_f32_e32 v76, 0xbfb8aa3b, v100
	v_exp_f32_e32 v101, v76
	v_cndmask_b32_e64 v76, v113, v103, s[40:41]
	v_cndmask_b32_e64 v77, v76, 0, vcc
	v_mov_b32_e32 v78, v79
	v_mov_b32_e32 v79, v87
	v_mov_b32_e32 v76, v91
	v_pk_mul_f32 v[76:77], v[78:79], v[76:77]
	v_cndmask_b32_e64 v78, v123, v112, s[42:43]
	v_cndmask_b32_e64 v78, v78, 0, s[50:51]
	v_fma_f32 v78, v83, v78, v95
	v_add_f32_e32 v77, v77, v78
	v_add_f32_e32 v78, v76, v77
	v_mul_f32_e32 v76, 0xbfb8aa3b, v78
	v_exp_f32_e32 v76, v76
	v_mul_f32_e32 v79, v57, v56
	v_add_f32_e32 v56, 1.0, v101
	v_rcp_f32_e32 v101, v56
	v_add_f32_e32 v56, 1.0, v76
	v_rcp_f32_e32 v102, v56
	v_cndmask_b32_e64 v56, v111, v96, s[40:41]
	v_mov_b32_e32 v76, v52
	v_cndmask_b32_e64 v52, v126, v110, s[42:43]
	v_cndmask_b32_e64 v57, v56, 0, vcc
	v_mov_b32_e32 v77, v64
	v_mov_b32_e32 v56, v68
	v_cndmask_b32_e64 v52, v52, 0, s[50:51]
	v_pk_mul_f32 v[56:57], v[76:77], v[56:57]
	v_fma_f32 v52, v60, v52, v72
	v_add_f32_e32 v52, v57, v52
	v_add_f32_e32 v76, v56, v52
	v_mul_f32_e32 v52, 0xbfb8aa3b, v76
	v_exp_f32_e32 v52, v52
	v_mul_f32_e32 v56, v100, v101
	v_mul_f32_e32 v77, v78, v102
	v_mul_f32_e32 v58, v58, v56
	v_add_f32_e32 v52, 1.0, v52
	v_rcp_f32_e32 v78, v52
	v_cndmask_b32_e64 v52, v109, v97, s[40:41]
	v_cndmask_b32_e64 v57, v52, 0, vcc
	v_mov_b32_e32 v52, v53
	v_mov_b32_e32 v53, v65
	v_mov_b32_e32 v56, v69
	v_pk_mul_f32 v[52:53], v[52:53], v[56:57]
	v_cndmask_b32_e64 v56, v124, v108, s[42:43]
	v_cndmask_b32_e64 v56, v56, 0, s[50:51]
	v_fma_f32 v56, v61, v56, v73
	v_add_f32_e32 v53, v53, v56
	v_add_f32_e32 v96, v52, v53
	v_mul_f32_e32 v52, 0xbfb8aa3b, v96
	v_exp_f32_e32 v52, v52
	v_mul_f32_e32 v53, v76, v78
	v_mul_f32_e32 v76, v48, v53
	v_mov_b32_e32 v56, v54
	v_add_f32_e32 v48, 1.0, v52
	v_cndmask_b32_e64 v52, v107, v98, s[40:41]
	v_cndmask_b32_e64 v54, v121, v106, s[42:43]
	v_cndmask_b32_e64 v53, v52, 0, vcc
	v_mov_b32_e32 v57, v66
	v_mov_b32_e32 v52, v70
	v_cndmask_b32_e64 v54, v54, 0, s[50:51]
	v_pk_mul_f32 v[52:53], v[56:57], v[52:53]
	v_fma_f32 v54, v62, v54, v74
	v_add_f32_e32 v53, v53, v54
	v_add_f32_e32 v56, v52, v53
	v_mul_f32_e32 v52, 0xbfb8aa3b, v56
	v_exp_f32_e32 v57, v52
	v_cndmask_b32_e64 v52, v105, v99, s[40:41]
	v_cndmask_b32_e64 v53, v52, 0, vcc
	v_mov_b32_e32 v54, v55
	v_mov_b32_e32 v55, v67
	v_mov_b32_e32 v52, v71
	v_pk_mul_f32 v[52:53], v[54:55], v[52:53]
	v_cndmask_b32_e64 v54, v120, v104, s[42:43]
	v_cndmask_b32_e64 v54, v54, 0, s[50:51]
	v_fma_f32 v54, v63, v54, v75
	v_add_f32_e32 v53, v53, v54
	v_add_f32_e32 v52, v52, v53
	v_mul_f32_e32 v53, 0xbfb8aa3b, v52
	v_exp_f32_e32 v53, v53
	v_rcp_f32_e32 v48, v48
	v_add_f32_e32 v54, 1.0, v57
	v_rcp_f32_e32 v54, v54
	v_add_f32_e32 v53, 1.0, v53
	v_rcp_f32_e32 v53, v53
	v_mul_f32_e32 v48, v96, v48
	v_mul_f32_e32 v55, v49, v48
	v_mul_f32_e32 v48, v56, v54
	v_mul_f32_e32 v54, v50, v48
	v_mul_f32_e32 v48, v52, v53
	v_mov_b64_e32 v[52:53], s[4:5]
	s_movk_i32 s50, 0x1600
	v_mul_f32_e32 v59, v59, v77
	v_mul_f32_e32 v51, v51, v48
	v_mad_i64_i32 v[52:53], s[50:51], v122, s50, v[52:53]
	v_cvt_pk_bf16_f32 v48, v127, v79
	v_cvt_pk_bf16_f32 v49, v58, v59
	v_cvt_pk_bf16_f32 v50, v76, v55
	v_cvt_pk_bf16_f32 v51, v54, v51
	v_lshl_add_u64 v[52:53], v[178:179], 1, v[52:53]
	global_store_dwordx4 v[52:53], v[48:51], off
; DI u32x4 pack8(const float (&f)[8]) { u32x4 w; w.x = pk2(f[0], f[1]); w.y = pk2(f[2], f[3]); w.z = pk2(f[4], f[5]); w.w = pk2(f[6], f[7]); return w; }
; DI float fsilu(float x) { return x * fsigmoid(x); }
; DI float dpp_ror1(float v) { return __int_as_float(__builtin_amdgcn_update_dpp(0, __float_as_int(v), 0x121, 0xf, 0xf, false)); }
; DI float dpp_ror2(float v) { return __int_as_float(__builtin_amdgcn_update_dpp(0, __float_as_int(v), 0x122, 0xf, 0xf, false)); }
;     DI void operator()(const f32x4 (&acc)[2][2][4][2], const pg8::Unit& u, int wr, int wcv, int fr, int fq) const {
;     ...
;             for (int m = 0; m < 4; ++m) {
;                 const int lrow = 64 * blk + 16 * m + fr, t = 254 * u.pm - 2 + lrow, spos = t & 2047;
;                 float o[8], r1[8], r2[8];
; #pragma unroll
;                 for (int e = 0; e < 8; ++e) { const float uc = acc[ai][0][m][e >> 2][e & 3], gv = acc[ai][1][m][e >> 2][e & 3];
;                     r1[e] = dpp_ror1(uc); r2[e] = dpp_ror2(uc);
;                     float um1 = (fr >= 1) ? r1[e] : p1[e], um2 = (fr >= 2) ? r2[e] : p2[e];
;                     if (spos < 1) um1 = 0.f;
;                     if (spos < 2) um2 = 0.f;
;                     const float v = bb[e] + w0[e] * um2 + w1[e] * um1 + w2[e] * uc;
;                     o[e] = fsilu(v) * gv; }
; #pragma unroll
;                 for (int e = 0; e < 8; ++e) { p1[e] = r1[e]; p2[e] = r2[e]; }
;                 if (lrow >= 2 && t < T) *(u32x4*)(act + (size_t)t * DFF + ch0) = pack8(o);
.LBB0_895:
	s_or_b64 exec, exec, s[58:59]
	v_add_u32_e32 v96, s53, v187
	v_mov_b32_e32 v79, v197
	v_mov_b32_e32 v78, v197
	v_mov_b32_e32 v77, v197
	v_mov_b32_e32 v76, v197
	v_mov_b32_e32 v59, v197
	v_mov_b32_e32 v58, v197
	v_mov_b32_e32 v57, v197
	v_mov_b32_e32 v56, v197
	v_mov_b32_e32 v55, v197
	v_mov_b32_e32 v54, v197
	v_mov_b32_e32 v53, v197
	v_mov_b32_e32 v52, v197
	v_mov_b32_e32 v51, v197
	v_mov_b32_e32 v50, v197
	v_mov_b32_e32 v49, v197
	v_mov_b32_e32 v48, v197
	v_cmp_gt_i32_e32 vcc, s19, v96
	v_mov_b32_dpp v79, v44 row_ror:1 row_mask:0xf bank_mask:0xf
	v_mov_b32_dpp v78, v44 row_ror:2 row_mask:0xf bank_mask:0xf
	v_mov_b32_dpp v77, v45 row_ror:1 row_mask:0xf bank_mask:0xf
	v_mov_b32_dpp v76, v45 row_ror:2 row_mask:0xf bank_mask:0xf
	v_mov_b32_dpp v59, v46 row_ror:1 row_mask:0xf bank_mask:0xf
	v_mov_b32_dpp v58, v46 row_ror:2 row_mask:0xf bank_mask:0xf
	v_mov_b32_dpp v57, v47 row_ror:1 row_mask:0xf bank_mask:0xf
	v_mov_b32_dpp v56, v47 row_ror:2 row_mask:0xf bank_mask:0xf
	v_mov_b32_dpp v55, v36 row_ror:1 row_mask:0xf bank_mask:0xf
	v_mov_b32_dpp v54, v36 row_ror:2 row_mask:0xf bank_mask:0xf
	v_mov_b32_dpp v53, v37 row_ror:1 row_mask:0xf bank_mask:0xf
	v_mov_b32_dpp v52, v37 row_ror:2 row_mask:0xf bank_mask:0xf
	v_mov_b32_dpp v51, v38 row_ror:1 row_mask:0xf bank_mask:0xf
	v_mov_b32_dpp v50, v38 row_ror:2 row_mask:0xf bank_mask:0xf
	v_mov_b32_dpp v49, v39 row_ror:1 row_mask:0xf bank_mask:0xf
	v_mov_b32_dpp v48, v39 row_ror:2 row_mask:0xf bank_mask:0xf
	s_and_b64 s[50:51], s[34:35], vcc
	s_and_saveexec_b64 s[58:59], s[50:51]
	s_cbranch_execz .LBB0_897
	v_and_b32_e32 v97, 0x7ff, v96
	v_cndmask_b32_e64 v98, v79, v119, s[40:41]
	v_cmp_eq_u32_e32 vcc, 0, v97
	v_mov_b32_e32 v100, v44
	v_cndmask_b32_e64 v44, v118, v78, s[42:43]
	v_cmp_gt_u32_e64 s[50:51], 2, v97
	v_cndmask_b32_e64 v99, v98, 0, vcc
	v_mov_b32_e32 v101, v84
	v_mov_b32_e32 v98, v88
	v_cndmask_b32_e64 v44, v44, 0, s[50:51]
	v_pk_mul_f32 v[98:99], v[100:101], v[98:99]
	v_fma_f32 v44, v80, v44, v92
	v_add_f32_e32 v44, v99, v44
	v_add_f32_e32 v97, v98, v44
	v_mul_f32_e32 v44, 0xbfb8aa3b, v97
	v_exp_f32_e32 v100, v44
	v_cndmask_b32_e64 v44, v77, v117, s[40:41]
	v_cndmask_b32_e64 v99, v44, 0, vcc
	v_mov_b32_e32 v44, v45
	v_mov_b32_e32 v45, v85
	v_mov_b32_e32 v98, v89
	v_pk_mul_f32 v[44:45], v[44:45], v[98:99]
	v_cndmask_b32_e64 v98, v116, v76, s[42:43]
	v_cndmask_b32_e64 v98, v98, 0, s[50:51]
	v_fma_f32 v98, v81, v98, v93
	v_add_f32_e32 v45, v45, v98
	v_add_f32_e32 v44, v44, v45
	v_mul_f32_e32 v45, 0xbfb8aa3b, v44
	v_exp_f32_e32 v45, v45
	v_add_f32_e32 v98, 1.0, v100
	v_rcp_f32_e32 v98, v98
	v_mov_b32_e32 v99, v86
	v_add_f32_e32 v45, 1.0, v45
	v_rcp_f32_e32 v45, v45
	v_mul_f32_e32 v97, v97, v98
	v_mul_f32_e32 v97, v40, v97
	v_mov_b32_e32 v98, v46
	v_mul_f32_e32 v40, v44, v45
	v_cndmask_b32_e64 v44, v59, v115, s[40:41]
	v_cndmask_b32_e64 v46, v114, v58, s[42:43]
	v_cndmask_b32_e64 v45, v44, 0, vcc
	v_mov_b32_e32 v44, v90
	v_cndmask_b32_e64 v46, v46, 0, s[50:51]
	v_pk_mul_f32 v[44:45], v[98:99], v[44:45]
	v_fma_f32 v46, v82, v46, v94
	v_add_f32_e32 v45, v45, v46
	v_add_f32_e32 v98, v44, v45
	v_mul_f32_e32 v44, 0xbfb8aa3b, v98
	v_exp_f32_e32 v99, v44
	v_cndmask_b32_e64 v44, v57, v113, s[40:41]
	v_cndmask_b32_e64 v45, v44, 0, vcc
	v_mov_b32_e32 v46, v47
	v_mov_b32_e32 v47, v87
	v_mov_b32_e32 v44, v91
	v_pk_mul_f32 v[44:45], v[46:47], v[44:45]
	v_cndmask_b32_e64 v46, v112, v56, s[42:43]
	v_cndmask_b32_e64 v46, v46, 0, s[50:51]
	v_fma_f32 v46, v83, v46, v95
	v_add_f32_e32 v45, v45, v46
	v_add_f32_e32 v46, v44, v45
	v_mul_f32_e32 v44, 0xbfb8aa3b, v46
	v_exp_f32_e32 v44, v44
	v_mul_f32_e32 v47, v41, v40
	v_add_f32_e32 v40, 1.0, v99
	v_rcp_f32_e32 v99, v40
	v_add_f32_e32 v40, 1.0, v44
	v_rcp_f32_e32 v100, v40
	v_cndmask_b32_e64 v40, v55, v111, s[40:41]
	v_mov_b32_e32 v44, v36
	v_cndmask_b32_e64 v36, v110, v54, s[42:43]
	v_cndmask_b32_e64 v41, v40, 0, vcc
	v_mov_b32_e32 v45, v64
	v_mov_b32_e32 v40, v68
	v_cndmask_b32_e64 v36, v36, 0, s[50:51]
	v_pk_mul_f32 v[40:41], v[44:45], v[40:41]
	v_fma_f32 v36, v60, v36, v72
	v_add_f32_e32 v36, v41, v36
	v_add_f32_e32 v44, v40, v36
	v_mul_f32_e32 v36, 0xbfb8aa3b, v44
	v_exp_f32_e32 v36, v36
	v_mul_f32_e32 v40, v98, v99
	v_mul_f32_e32 v45, v46, v100
	v_mul_f32_e32 v42, v42, v40
	v_add_f32_e32 v36, 1.0, v36
	v_rcp_f32_e32 v46, v36
	v_cndmask_b32_e64 v36, v53, v109, s[40:41]
	v_cndmask_b32_e64 v41, v36, 0, vcc
	v_mov_b32_e32 v36, v37
	v_mov_b32_e32 v37, v65
	v_mov_b32_e32 v40, v69
	v_pk_mul_f32 v[36:37], v[36:37], v[40:41]
	v_cndmask_b32_e64 v40, v108, v52, s[42:43]
	v_cndmask_b32_e64 v40, v40, 0, s[50:51]
	v_fma_f32 v40, v61, v40, v73
	v_add_f32_e32 v37, v37, v40
	v_add_f32_e32 v98, v36, v37
	v_mul_f32_e32 v36, 0xbfb8aa3b, v98
	v_exp_f32_e32 v36, v36
	v_mul_f32_e32 v37, v44, v46
	v_mul_f32_e32 v44, v32, v37
	v_mov_b32_e32 v40, v38
	v_add_f32_e32 v32, 1.0, v36
	v_cndmask_b32_e64 v36, v51, v107, s[40:41]
	v_cndmask_b32_e64 v38, v106, v50, s[42:43]
	v_cndmask_b32_e64 v37, v36, 0, vcc
	v_mov_b32_e32 v41, v66
	v_mov_b32_e32 v36, v70
	v_cndmask_b32_e64 v38, v38, 0, s[50:51]
	v_pk_mul_f32 v[36:37], v[40:41], v[36:37]
	v_fma_f32 v38, v62, v38, v74
	v_add_f32_e32 v37, v37, v38
	v_add_f32_e32 v40, v36, v37
	v_mul_f32_e32 v36, 0xbfb8aa3b, v40
	v_exp_f32_e32 v41, v36
	v_cndmask_b32_e64 v36, v49, v105, s[40:41]
	v_cndmask_b32_e64 v37, v36, 0, vcc
	v_mov_b32_e32 v38, v39
	v_mov_b32_e32 v39, v67
	v_mov_b32_e32 v36, v71
	v_pk_mul_f32 v[36:37], v[38:39], v[36:37]
	v_cndmask_b32_e64 v38, v104, v48, s[42:43]
	v_cndmask_b32_e64 v38, v38, 0, s[50:51]
	v_fma_f32 v38, v63, v38, v75
	v_add_f32_e32 v37, v37, v38
	v_add_f32_e32 v36, v36, v37
	v_mul_f32_e32 v37, 0xbfb8aa3b, v36
	v_exp_f32_e32 v37, v37
	v_rcp_f32_e32 v32, v32
	v_add_f32_e32 v38, 1.0, v41
	v_rcp_f32_e32 v38, v38
	v_add_f32_e32 v37, 1.0, v37
	v_rcp_f32_e32 v37, v37
	v_mul_f32_e32 v32, v98, v32
	v_mul_f32_e32 v39, v33, v32
	v_mul_f32_e32 v32, v40, v38
	v_mul_f32_e32 v38, v34, v32
	v_mul_f32_e32 v32, v36, v37
	v_mov_b64_e32 v[36:37], s[4:5]
	s_movk_i32 s50, 0x1600
	v_mul_f32_e32 v43, v43, v45
	v_mul_f32_e32 v35, v35, v32
	v_mad_i64_i32 v[36:37], s[50:51], v96, s50, v[36:37]
	v_cvt_pk_bf16_f32 v32, v97, v47
	v_cvt_pk_bf16_f32 v33, v42, v43
	v_cvt_pk_bf16_f32 v34, v44, v39
	v_cvt_pk_bf16_f32 v35, v38, v35
	v_lshl_add_u64 v[36:37], v[178:179], 1, v[36:37]
	global_store_dwordx4 v[36:37], v[32:35], off
; DI u32x4 pack8(const float (&f)[8]) { u32x4 w; w.x = pk2(f[0], f[1]); w.y = pk2(f[2], f[3]); w.z = pk2(f[4], f[5]); w.w = pk2(f[6], f[7]); return w; }
; DI float fsilu(float x) { return x * fsigmoid(x); }
; DI float dpp_ror1(float v) { return __int_as_float(__builtin_amdgcn_update_dpp(0, __float_as_int(v), 0x121, 0xf, 0xf, false)); }
; DI float dpp_ror2(float v) { return __int_as_float(__builtin_amdgcn_update_dpp(0, __float_as_int(v), 0x122, 0xf, 0xf, false)); }
;     DI void operator()(const f32x4 (&acc)[2][2][4][2], const pg8::Unit& u, int wr, int wcv, int fr, int fq) const {
;     ...
;             for (int m = 0; m < 4; ++m) {
;                 const int lrow = 64 * blk + 16 * m + fr, t = 254 * u.pm - 2 + lrow, spos = t & 2047;
;                 float o[8], r1[8], r2[8];
; #pragma unroll
;                 for (int e = 0; e < 8; ++e) { const float uc = acc[ai][0][m][e >> 2][e & 3], gv = acc[ai][1][m][e >> 2][e & 3];
;                     r1[e] = dpp_ror1(uc); r2[e] = dpp_ror2(uc);
;                     float um1 = (fr >= 1) ? r1[e] : p1[e], um2 = (fr >= 2) ? r2[e] : p2[e];
;                     if (spos < 1) um1 = 0.f;
;                     if (spos < 2) um2 = 0.f;
;                     const float v = bb[e] + w0[e] * um2 + w1[e] * um1 + w2[e] * uc;
;                     o[e] = fsilu(v) * gv; }
; #pragma unroll
;                 for (int e = 0; e < 8; ++e) { p1[e] = r1[e]; p2[e] = r2[e]; }
;                 if (lrow >= 2 && t < T) *(u32x4*)(act + (size_t)t * DFF + ch0) = pack8(o);
.LBB0_897:
	s_or_b64 exec, exec, s[58:59]
	v_add_u32_e32 v96, s53, v188
	v_mov_b32_e32 v46, v197
	v_mov_b32_e32 v44, v197
	v_mov_b32_e32 v47, v197
	v_mov_b32_e32 v45, v197
	v_mov_b32_e32 v42, v197
	v_mov_b32_e32 v40, v197
	v_mov_b32_e32 v43, v197
	v_mov_b32_e32 v41, v197
	v_mov_b32_e32 v38, v197
	v_mov_b32_e32 v36, v197
	v_mov_b32_e32 v39, v197
	v_mov_b32_e32 v37, v197
	v_mov_b32_e32 v34, v197
	v_mov_b32_e32 v32, v197
	v_mov_b32_e32 v35, v197
	v_mov_b32_e32 v33, v197
	v_cmp_gt_i32_e32 vcc, s19, v96
	v_mov_b32_dpp v46, v28 row_ror:1 row_mask:0xf bank_mask:0xf
	v_mov_b32_dpp v44, v28 row_ror:2 row_mask:0xf bank_mask:0xf
	v_mov_b32_dpp v47, v29 row_ror:1 row_mask:0xf bank_mask:0xf
	v_mov_b32_dpp v45, v29 row_ror:2 row_mask:0xf bank_mask:0xf
	v_mov_b32_dpp v42, v30 row_ror:1 row_mask:0xf bank_mask:0xf
	v_mov_b32_dpp v40, v30 row_ror:2 row_mask:0xf bank_mask:0xf
	v_mov_b32_dpp v43, v31 row_ror:1 row_mask:0xf bank_mask:0xf
	v_mov_b32_dpp v41, v31 row_ror:2 row_mask:0xf bank_mask:0xf
	v_mov_b32_dpp v38, v20 row_ror:1 row_mask:0xf bank_mask:0xf
	v_mov_b32_dpp v36, v20 row_ror:2 row_mask:0xf bank_mask:0xf
	v_mov_b32_dpp v39, v21 row_ror:1 row_mask:0xf bank_mask:0xf
	v_mov_b32_dpp v37, v21 row_ror:2 row_mask:0xf bank_mask:0xf
	v_mov_b32_dpp v34, v22 row_ror:1 row_mask:0xf bank_mask:0xf
	v_mov_b32_dpp v32, v22 row_ror:2 row_mask:0xf bank_mask:0xf
	v_mov_b32_dpp v35, v23 row_ror:1 row_mask:0xf bank_mask:0xf
	v_mov_b32_dpp v33, v23 row_ror:2 row_mask:0xf bank_mask:0xf
	s_and_b64 s[50:51], s[34:35], vcc
	s_and_saveexec_b64 s[58:59], s[50:51]
	s_cbranch_execz .LBB0_899
	v_and_b32_e32 v97, 0x7ff, v96
	v_cndmask_b32_e64 v79, v46, v79, s[40:41]
	v_cmp_eq_u32_e32 vcc, 0, v97
	v_mov_b32_e32 v100, v28
	v_cndmask_b32_e64 v28, v78, v44, s[42:43]
	v_cmp_gt_u32_e64 s[50:51], 2, v97
	v_cndmask_b32_e64 v99, v79, 0, vcc
	v_mov_b32_e32 v101, v84
	v_mov_b32_e32 v98, v88
	v_cndmask_b32_e64 v28, v28, 0, s[50:51]
	v_pk_mul_f32 v[98:99], v[100:101], v[98:99]
	v_fma_f32 v28, v80, v28, v92
	v_add_f32_e32 v28, v99, v28
	v_add_f32_e32 v97, v98, v28
	v_mul_f32_e32 v28, 0xbfb8aa3b, v97
	v_exp_f32_e32 v98, v28
	v_cndmask_b32_e64 v28, v47, v77, s[40:41]
	v_cndmask_b32_e64 v76, v76, v45, s[42:43]
	v_cndmask_b32_e64 v79, v28, 0, vcc
	v_mov_b32_e32 v28, v29
	v_mov_b32_e32 v29, v85
	v_mov_b32_e32 v78, v89
	v_cndmask_b32_e64 v76, v76, 0, s[50:51]
	v_pk_mul_f32 v[28:29], v[28:29], v[78:79]
	v_fma_f32 v76, v81, v76, v93
	v_add_f32_e32 v29, v29, v76
	v_add_f32_e32 v28, v28, v29
	v_mul_f32_e32 v29, 0xbfb8aa3b, v28
	v_exp_f32_e32 v29, v29
	v_add_f32_e32 v76, 1.0, v98
	v_rcp_f32_e32 v76, v76
	v_mov_b32_e32 v77, v86
	v_add_f32_e32 v29, 1.0, v29
	v_rcp_f32_e32 v29, v29
	v_mul_f32_e32 v76, v97, v76
	v_mul_f32_e32 v78, v24, v76
	v_mov_b32_e32 v76, v30
	v_mul_f32_e32 v24, v28, v29
	v_cndmask_b32_e64 v28, v42, v59, s[40:41]
	v_cndmask_b32_e64 v30, v58, v40, s[42:43]
	v_cndmask_b32_e64 v29, v28, 0, vcc
	v_mov_b32_e32 v28, v90
	v_cndmask_b32_e64 v30, v30, 0, s[50:51]
	v_pk_mul_f32 v[28:29], v[76:77], v[28:29]
	v_fma_f32 v30, v82, v30, v94
	v_add_f32_e32 v29, v29, v30
	v_add_f32_e32 v58, v28, v29
	v_mul_f32_e32 v28, 0xbfb8aa3b, v58
	v_exp_f32_e32 v59, v28
	v_cndmask_b32_e64 v28, v43, v57, s[40:41]
	v_cndmask_b32_e64 v29, v28, 0, vcc
	v_mov_b32_e32 v30, v31
	v_mov_b32_e32 v31, v87
	v_mov_b32_e32 v28, v91
	v_pk_mul_f32 v[28:29], v[30:31], v[28:29]
	v_cndmask_b32_e64 v30, v56, v41, s[42:43]
	v_cndmask_b32_e64 v30, v30, 0, s[50:51]
	v_fma_f32 v30, v83, v30, v95
	v_add_f32_e32 v29, v29, v30
	v_add_f32_e32 v30, v28, v29
	v_mul_f32_e32 v28, 0xbfb8aa3b, v30
	v_exp_f32_e32 v28, v28
	v_mul_f32_e32 v31, v25, v24
	v_add_f32_e32 v24, 1.0, v59
	v_rcp_f32_e32 v56, v24
	v_add_f32_e32 v24, 1.0, v28
	v_rcp_f32_e32 v57, v24
	v_cndmask_b32_e64 v24, v38, v55, s[40:41]
	v_mov_b32_e32 v28, v20
	v_cndmask_b32_e64 v20, v54, v36, s[42:43]
	v_cndmask_b32_e64 v25, v24, 0, vcc
	v_mov_b32_e32 v29, v64
	v_mov_b32_e32 v24, v68
	v_cndmask_b32_e64 v20, v20, 0, s[50:51]
	v_pk_mul_f32 v[24:25], v[28:29], v[24:25]
	v_fma_f32 v20, v60, v20, v72
	v_add_f32_e32 v20, v25, v20
	v_add_f32_e32 v28, v24, v20
	v_mul_f32_e32 v20, 0xbfb8aa3b, v28
	v_exp_f32_e32 v20, v20
	v_mul_f32_e32 v24, v58, v56
	v_mul_f32_e32 v29, v30, v57
	v_mul_f32_e32 v26, v26, v24
	v_add_f32_e32 v20, 1.0, v20
	v_rcp_f32_e32 v30, v20
	v_cndmask_b32_e64 v20, v39, v53, s[40:41]
	v_cndmask_b32_e64 v25, v20, 0, vcc
	v_mov_b32_e32 v20, v21
	v_mov_b32_e32 v21, v65
	v_mov_b32_e32 v24, v69
	v_pk_mul_f32 v[20:21], v[20:21], v[24:25]
	v_cndmask_b32_e64 v24, v52, v37, s[42:43]
	v_cndmask_b32_e64 v24, v24, 0, s[50:51]
	v_fma_f32 v24, v61, v24, v73
	v_add_f32_e32 v21, v21, v24
	v_add_f32_e32 v52, v20, v21
	v_mul_f32_e32 v20, 0xbfb8aa3b, v52
	v_exp_f32_e32 v20, v20
	v_mul_f32_e32 v21, v28, v30
	v_mul_f32_e32 v28, v16, v21
	v_mov_b32_e32 v24, v22
	v_add_f32_e32 v16, 1.0, v20
	v_cndmask_b32_e64 v20, v34, v51, s[40:41]
	v_cndmask_b32_e64 v22, v50, v32, s[42:43]
	v_cndmask_b32_e64 v21, v20, 0, vcc
	v_mov_b32_e32 v25, v66
	v_mov_b32_e32 v20, v70
	v_cndmask_b32_e64 v22, v22, 0, s[50:51]
	v_pk_mul_f32 v[20:21], v[24:25], v[20:21]
	v_fma_f32 v22, v62, v22, v74
	v_add_f32_e32 v21, v21, v22
	v_add_f32_e32 v24, v20, v21
	v_mul_f32_e32 v20, 0xbfb8aa3b, v24
	v_exp_f32_e32 v25, v20
	v_cndmask_b32_e64 v20, v35, v49, s[40:41]
	v_cndmask_b32_e64 v21, v20, 0, vcc
	v_mov_b32_e32 v22, v23
	v_mov_b32_e32 v23, v67
	v_mov_b32_e32 v20, v71
	v_pk_mul_f32 v[20:21], v[22:23], v[20:21]
	v_cndmask_b32_e64 v22, v48, v33, s[42:43]
	v_cndmask_b32_e64 v22, v22, 0, s[50:51]
	v_fma_f32 v22, v63, v22, v75
	v_add_f32_e32 v21, v21, v22
	v_add_f32_e32 v20, v20, v21
	v_mul_f32_e32 v21, 0xbfb8aa3b, v20
	v_exp_f32_e32 v21, v21
	v_rcp_f32_e32 v16, v16
	v_add_f32_e32 v22, 1.0, v25
	v_rcp_f32_e32 v22, v22
	v_add_f32_e32 v21, 1.0, v21
	v_rcp_f32_e32 v21, v21
	v_mul_f32_e32 v16, v52, v16
	v_mul_f32_e32 v23, v17, v16
	v_mul_f32_e32 v16, v24, v22
	v_mul_f32_e32 v22, v18, v16
	v_mul_f32_e32 v16, v20, v21
	v_mov_b64_e32 v[20:21], s[4:5]
	s_movk_i32 s50, 0x1600
	v_mul_f32_e32 v27, v27, v29
	v_mul_f32_e32 v19, v19, v16
	v_mad_i64_i32 v[20:21], s[50:51], v96, s50, v[20:21]
	v_cvt_pk_bf16_f32 v16, v78, v31
	v_cvt_pk_bf16_f32 v17, v26, v27
	v_cvt_pk_bf16_f32 v18, v28, v23
	v_cvt_pk_bf16_f32 v19, v22, v19
	v_lshl_add_u64 v[20:21], v[178:179], 1, v[20:21]
	global_store_dwordx4 v[20:21], v[16:19], off
; DI u32x4 pack8(const float (&f)[8]) { u32x4 w; w.x = pk2(f[0], f[1]); w.y = pk2(f[2], f[3]); w.z = pk2(f[4], f[5]); w.w = pk2(f[6], f[7]); return w; }
; DI float fsilu(float x) { return x * fsigmoid(x); }
; DI float dpp_ror1(float v) { return __int_as_float(__builtin_amdgcn_update_dpp(0, __float_as_int(v), 0x121, 0xf, 0xf, false)); }
; DI float dpp_ror2(float v) { return __int_as_float(__builtin_amdgcn_update_dpp(0, __float_as_int(v), 0x122, 0xf, 0xf, false)); }
;     DI void operator()(const f32x4 (&acc)[2][2][4][2], const pg8::Unit& u, int wr, int wcv, int fr, int fq) const {
;     ...
;             for (int m = 0; m < 4; ++m) {
;                 const int lrow = 64 * blk + 16 * m + fr, t = 254 * u.pm - 2 + lrow, spos = t & 2047;
;                 float o[8], r1[8], r2[8];
; #pragma unroll
;                 for (int e = 0; e < 8; ++e) { const float uc = acc[ai][0][m][e >> 2][e & 3], gv = acc[ai][1][m][e >> 2][e & 3];
;                     r1[e] = dpp_ror1(uc); r2[e] = dpp_ror2(uc);
;                     float um1 = (fr >= 1) ? r1[e] : p1[e], um2 = (fr >= 2) ? r2[e] : p2[e];
;                     if (spos < 1) um1 = 0.f;
;                     if (spos < 2) um2 = 0.f;
;                     const float v = bb[e] + w0[e] * um2 + w1[e] * um1 + w2[e] * uc;
;                     o[e] = fsilu(v) * gv; }
; #pragma unroll
;                 for (int e = 0; e < 8; ++e) { p1[e] = r1[e]; p2[e] = r2[e]; }
;                 if (lrow >= 2 && t < T) *(u32x4*)(act + (size_t)t * DFF + ch0) = pack8(o);
.LBB0_899:
	s_or_b64 exec, exec, s[58:59]
	s_nop 0
	v_add_u32_e32 v16, s53, v189
	v_mov_b32_e32 v31, v197
	v_mov_b32_e32 v29, v197
	v_mov_b32_e32 v48, v197
	v_mov_b32_e32 v30, v197
	v_mov_b32_e32 v27, v197
	v_mov_b32_e32 v25, v197
	v_mov_b32_e32 v28, v197
	v_mov_b32_e32 v26, v197
	v_mov_b32_e32 v23, v197
	v_mov_b32_e32 v21, v197
	v_mov_b32_e32 v24, v197
	v_mov_b32_e32 v22, v197
	v_mov_b32_e32 v19, v197
	v_mov_b32_e32 v17, v197
	v_mov_b32_e32 v20, v197
	v_mov_b32_e32 v18, v197
	v_cmp_gt_i32_e32 vcc, s19, v16
	v_mov_b32_dpp v31, v12 row_ror:1 row_mask:0xf bank_mask:0xf
	v_mov_b32_dpp v29, v12 row_ror:2 row_mask:0xf bank_mask:0xf
	v_mov_b32_dpp v48, v13 row_ror:1 row_mask:0xf bank_mask:0xf
	v_mov_b32_dpp v30, v13 row_ror:2 row_mask:0xf bank_mask:0xf
	v_mov_b32_dpp v27, v14 row_ror:1 row_mask:0xf bank_mask:0xf
	v_mov_b32_dpp v25, v14 row_ror:2 row_mask:0xf bank_mask:0xf
	v_mov_b32_dpp v28, v15 row_ror:1 row_mask:0xf bank_mask:0xf
	v_mov_b32_dpp v26, v15 row_ror:2 row_mask:0xf bank_mask:0xf
	v_mov_b32_dpp v23, v4 row_ror:1 row_mask:0xf bank_mask:0xf
	v_mov_b32_dpp v21, v4 row_ror:2 row_mask:0xf bank_mask:0xf
	v_mov_b32_dpp v24, v5 row_ror:1 row_mask:0xf bank_mask:0xf
	v_mov_b32_dpp v22, v5 row_ror:2 row_mask:0xf bank_mask:0xf
	v_mov_b32_dpp v19, v6 row_ror:1 row_mask:0xf bank_mask:0xf
	v_mov_b32_dpp v17, v6 row_ror:2 row_mask:0xf bank_mask:0xf
	v_mov_b32_dpp v20, v7 row_ror:1 row_mask:0xf bank_mask:0xf
	v_mov_b32_dpp v18, v7 row_ror:2 row_mask:0xf bank_mask:0xf
	s_and_b64 s[50:51], s[34:35], vcc
	s_and_saveexec_b64 s[58:59], s[50:51]
	s_cbranch_execz .LBB0_901
	v_and_b32_e32 v49, 0x7ff, v16
	v_cmp_eq_u32_e64 s[50:51], 0, v49
	v_cmp_gt_u32_e32 vcc, 2, v49
	v_cndmask_b32_e64 v31, v31, v46, s[40:41]
	v_cndmask_b32_e64 v46, v48, v47, s[40:41]
	v_cndmask_b32_e64 v29, v44, v29, s[42:43]
	v_cndmask_b32_e64 v30, v45, v30, s[42:43]
	v_cndmask_b32_e64 v47, v46, 0, s[50:51]
	v_cndmask_b32_e64 v46, v31, 0, s[50:51]
	v_cndmask_b32_e64 v31, v30, 0, vcc
	v_cndmask_b32_e64 v30, v29, 0, vcc
	v_pk_fma_f32 v[30:31], v[80:81], v[30:31], v[92:93]
	v_cndmask_b32_e64 v25, v40, v25, s[42:43]
	v_pk_fma_f32 v[30:31], v[84:85], v[46:47], v[30:31]
	v_cndmask_b32_e64 v26, v41, v26, s[42:43]
	v_pk_fma_f32 v[12:13], v[12:13], v[88:89], v[30:31]
	s_nop 0
	v_mul_f32_e32 v29, 0xbfb8aa3b, v12
	v_exp_f32_e32 v29, v29
	s_nop 0
	v_add_f32_e32 v29, 1.0, v29
	v_rcp_f32_e32 v30, v29
	v_mul_f32_e32 v29, 0xbfb8aa3b, v13
	v_exp_f32_e32 v29, v29
	s_nop 0
	v_add_f32_e32 v29, 1.0, v29
	v_rcp_f32_e32 v31, v29
	s_nop 0
	v_pk_mul_f32 v[12:13], v[12:13], v[30:31]
	s_nop 0
	v_pk_mul_f32 v[8:9], v[8:9], v[12:13]
	v_cndmask_b32_e64 v12, v27, v42, s[40:41]
	v_cndmask_b32_e64 v13, v28, v43, s[40:41]
	v_cndmask_b32_e64 v27, v26, 0, vcc
	v_cndmask_b32_e64 v26, v25, 0, vcc
	v_cndmask_b32_e64 v13, v13, 0, s[50:51]
	v_cndmask_b32_e64 v12, v12, 0, s[50:51]
	v_pk_fma_f32 v[26:27], v[82:83], v[26:27], v[94:95]
	s_nop 0
	v_pk_fma_f32 v[12:13], v[86:87], v[12:13], v[26:27]
	s_nop 0
	v_pk_fma_f32 v[12:13], v[14:15], v[90:91], v[12:13]
	s_nop 0
	v_mul_f32_e32 v14, 0xbfb8aa3b, v12
	v_mul_f32_e32 v15, 0xbfb8aa3b, v13
	v_exp_f32_e32 v14, v14
	v_exp_f32_e32 v15, v15
	v_add_f32_e32 v14, 1.0, v14
	v_add_f32_e32 v15, 1.0, v15
	v_rcp_f32_e32 v14, v14
	v_rcp_f32_e32 v15, v15
	s_nop 0
	v_pk_mul_f32 v[12:13], v[12:13], v[14:15]
	v_cndmask_b32_e64 v14, v36, v21, s[42:43]
	v_cndmask_b32_e64 v15, v37, v22, s[42:43]
	v_pk_mul_f32 v[10:11], v[10:11], v[12:13]
	v_cndmask_b32_e64 v12, v23, v38, s[40:41]
	v_cndmask_b32_e64 v13, v24, v39, s[40:41]
	v_cndmask_b32_e64 v15, v15, 0, vcc
	v_cndmask_b32_e64 v14, v14, 0, vcc
	v_cndmask_b32_e64 v13, v13, 0, s[50:51]
	v_cndmask_b32_e64 v12, v12, 0, s[50:51]
	v_pk_fma_f32 v[14:15], v[60:61], v[14:15], v[72:73]
	s_nop 0
	v_pk_fma_f32 v[12:13], v[64:65], v[12:13], v[14:15]
	s_nop 0
	v_pk_fma_f32 v[4:5], v[4:5], v[68:69], v[12:13]
	s_nop 0
	v_mul_f32_e32 v12, 0xbfb8aa3b, v4
	v_mul_f32_e32 v13, 0xbfb8aa3b, v5
	v_exp_f32_e32 v12, v12
	v_exp_f32_e32 v13, v13
	v_add_f32_e32 v12, 1.0, v12
	v_add_f32_e32 v13, 1.0, v13
	v_rcp_f32_e32 v12, v12
	v_rcp_f32_e32 v13, v13
	s_nop 0
	v_pk_mul_f32 v[4:5], v[4:5], v[12:13]
	v_cndmask_b32_e64 v12, v32, v17, s[42:43]
	v_cndmask_b32_e64 v13, v33, v18, s[42:43]
	v_pk_mul_f32 v[4:5], v[0:1], v[4:5]
	v_cndmask_b32_e64 v0, v19, v34, s[40:41]
	v_cndmask_b32_e64 v1, v20, v35, s[40:41]
	v_cndmask_b32_e64 v13, v13, 0, vcc
	v_cndmask_b32_e64 v12, v12, 0, vcc
	v_cndmask_b32_e64 v1, v1, 0, s[50:51]
	v_cndmask_b32_e64 v0, v0, 0, s[50:51]
	v_pk_fma_f32 v[12:13], v[62:63], v[12:13], v[74:75]
	s_movk_i32 s50, 0x1600
	v_pk_fma_f32 v[0:1], v[66:67], v[0:1], v[12:13]
	s_nop 0
	v_pk_fma_f32 v[0:1], v[6:7], v[70:71], v[0:1]
	s_nop 0
	v_mul_f32_e32 v6, 0xbfb8aa3b, v0
	v_mul_f32_e32 v7, 0xbfb8aa3b, v1
	v_exp_f32_e32 v6, v6
	v_exp_f32_e32 v7, v7
	v_add_f32_e32 v6, 1.0, v6
	v_add_f32_e32 v7, 1.0, v7
	v_rcp_f32_e32 v6, v6
	v_rcp_f32_e32 v7, v7
	s_nop 0
	v_pk_mul_f32 v[0:1], v[0:1], v[6:7]
	s_nop 0
	v_pk_mul_f32 v[6:7], v[2:3], v[0:1]
	v_cvt_pk_bf16_f32 v2, v4, v5
	v_mov_b64_e32 v[4:5], s[4:5]
	v_mad_i64_i32 v[4:5], s[50:51], v16, s50, v[4:5]
	v_cvt_pk_bf16_f32 v0, v8, v9
	v_cvt_pk_bf16_f32 v1, v10, v11
	v_cvt_pk_bf16_f32 v3, v6, v7
	v_lshl_add_u64 v[4:5], v[178:179], 1, v[4:5]
	global_store_dwordx4 v[4:5], v[0:3], off
